# skinny sample-row GEMMs: coalesced fragment fetch (4 lanes per row) + ds_bpermute to MFMA lanes (was texture-address bound)
# speedup vs baseline: 1.0488x; 1.0277x over previous
; #define LAS __attribute__((address_space(3)))
; template <int MODE> ...
;     const int fr = lane & 15, fq = lane >> 4, tw = wave & 3, kh = wave >> 2;
;     LAS f32x4* red = (LAS f32x4*)lds;
;     for (int T0 = bid * 4; T0 < 1024; T0 += G * 4) {
;         const int T = T0 + tw, rt = T >> 7, ct = T & 127;
;         f32x4 tot = (f32x4){0.f, 0.f, 0.f, 0.f};
;         if (MODE == 0) {
;             const int kb = kh * (K / 2);
;             const bf16_t* ap = A + (size_t)(rt * 16 + fr) * lda + kb + fq * 8;
;             const bf16_t* bp = Bt + (size_t)(ct * 16 + fr) * ldb + kb + fq * 8;
; #pragma unroll 16
;             for (int ks = 0; ks < K / 64; ++ks) {
;                 const bf16x8 af = *(const bf16x8*)(ap + ks * 32), bfv = *(const bf16x8*)(bp + ks * 32);
;                 tot = __builtin_amdgcn_mfma_f32_16x16x32_bf16(bfv, af, tot, 0, 0, 0);
;             }
.LBB0_218:
	v_mbcnt_lo_u32_b32 v128, -1, 0
	v_mbcnt_hi_u32_b32 v128, -1, v128
	v_lshrrev_b32_e32 v129, 2, v128
	v_and_b32_e32 v132, 15, v128
	v_sub_u32_e32 v129, v129, v132
	v_mul_i32_i24_e32 v130, 0x2c00, v129
	v_and_b32_e32 v133, 3, v128
	v_lshrrev_b32_e32 v135, 4, v128
	v_sub_u32_e32 v133, v133, v135
	v_lshlrev_b32_e32 v133, 4, v133
	v_add_u32_e32 v130, v130, v133
	v_ashrrev_i32_e32 v131, 31, v130
	v_lshl_or_b32 v134, v132, 2, v135
	v_lshlrev_b32_e32 v134, 2, v134
	s_and_b32 s14, s13, 0x7c
	s_or_b32 s14, s14, s56
	s_lshl_b32 s14, s14, 4
	v_or_b32_e32 v0, s14, v234
	v_mul_u32_u24_e32 v0, 0x1600, v0
	v_lshlrev_b32_e32 v4, 1, v0
	v_lshl_add_u64 v[2:3], v[8:9], 0, v[4:5]
	v_lshl_add_u64 v[2:3], v[2:3], 0, v[130:131]
	global_load_dwordx4 v[20:23], v[2:3], off
	s_ashr_i32 s15, s13, 3
	v_and_or_b32 v12, s15, -16, v234
	v_mad_i64_i32 v[0:1], s[20:21], v12, s17, v[6:7]
	v_lshl_add_u64 v[0:1], v[0:1], 0, v[130:131]
	global_load_dwordx4 v[24:27], v[0:1], off
	global_load_dwordx4 v[28:31], v[2:3], off offset:64
	global_load_dwordx4 v[32:35], v[0:1], off offset:64
	global_load_dwordx4 v[36:39], v[2:3], off offset:128
	global_load_dwordx4 v[40:43], v[2:3], off offset:192
	global_load_dwordx4 v[44:47], v[0:1], off offset:128
	global_load_dwordx4 v[48:51], v[0:1], off offset:192
	global_load_dwordx4 v[52:55], v[2:3], off offset:256
	global_load_dwordx4 v[56:59], v[2:3], off offset:320
	global_load_dwordx4 v[60:63], v[0:1], off offset:256
	global_load_dwordx4 v[64:67], v[0:1], off offset:320
	global_load_dwordx4 v[68:71], v[2:3], off offset:384
	global_load_dwordx4 v[72:75], v[2:3], off offset:448
	global_load_dwordx4 v[76:79], v[0:1], off offset:384
	global_load_dwordx4 v[80:83], v[0:1], off offset:448
	global_load_dwordx4 v[84:87], v[2:3], off offset:512
	global_load_dwordx4 v[88:91], v[2:3], off offset:576
	global_load_dwordx4 v[92:95], v[0:1], off offset:512
	global_load_dwordx4 v[96:99], v[0:1], off offset:576
	global_load_dwordx4 v[100:103], v[2:3], off offset:640
	global_load_dwordx4 v[104:107], v[0:1], off offset:640
	global_load_dwordx4 v[108:111], v[2:3], off offset:704
	global_load_dwordx4 v[112:115], v[0:1], off offset:704
	global_load_dwordx4 v[116:119], v[2:3], off offset:768
	global_load_dwordx4 v[120:123], v[2:3], off offset:832
	s_waitcnt vmcnt(24)
	ds_bpermute_b32 v20, v134, v20
	ds_bpermute_b32 v21, v134, v21
	ds_bpermute_b32 v22, v134, v22
	ds_bpermute_b32 v23, v134, v23
	ds_bpermute_b32 v24, v134, v24
	ds_bpermute_b32 v25, v134, v25
	ds_bpermute_b32 v26, v134, v26
	ds_bpermute_b32 v27, v134, v27
	s_waitcnt lgkmcnt(0)
	v_mfma_f32_16x16x32_bf16 v[20:23], v[20:23], v[24:27], 0
	global_load_dwordx4 v[24:27], v[0:1], off offset:768
	global_load_dwordx4 v[124:127], v[0:1], off offset:832
	s_waitcnt vmcnt(24)
	ds_bpermute_b32 v28, v134, v28
	ds_bpermute_b32 v29, v134, v29
	ds_bpermute_b32 v30, v134, v30
	ds_bpermute_b32 v31, v134, v31
	ds_bpermute_b32 v32, v134, v32
	ds_bpermute_b32 v33, v134, v33
	ds_bpermute_b32 v34, v134, v34
	ds_bpermute_b32 v35, v134, v35
	s_waitcnt lgkmcnt(0)
	v_mfma_f32_16x16x32_bf16 v[20:23], v[28:31], v[32:35], v[20:23]
	global_load_dwordx4 v[28:31], v[2:3], off offset:896
	global_load_dwordx4 v[32:35], v[0:1], off offset:896
	s_waitcnt vmcnt(23)
	ds_bpermute_b32 v36, v134, v36
	ds_bpermute_b32 v37, v134, v37
	ds_bpermute_b32 v38, v134, v38
	ds_bpermute_b32 v39, v134, v39
	ds_bpermute_b32 v44, v134, v44
	ds_bpermute_b32 v45, v134, v45
	ds_bpermute_b32 v46, v134, v46
	ds_bpermute_b32 v47, v134, v47
	s_waitcnt lgkmcnt(0)
	v_mfma_f32_16x16x32_bf16 v[20:23], v[36:39], v[44:47], v[20:23]
	global_load_dwordx4 v[36:39], v[2:3], off offset:960
	global_load_dwordx4 v[44:47], v[0:1], off offset:960
	s_waitcnt vmcnt(24)
	ds_bpermute_b32 v40, v134, v40
	ds_bpermute_b32 v41, v134, v41
	ds_bpermute_b32 v42, v134, v42
	ds_bpermute_b32 v43, v134, v43
	ds_bpermute_b32 v48, v134, v48
	ds_bpermute_b32 v49, v134, v49
	ds_bpermute_b32 v50, v134, v50
	ds_bpermute_b32 v51, v134, v51
	s_waitcnt lgkmcnt(0)
	v_mfma_f32_16x16x32_bf16 v[20:23], v[40:43], v[48:51], v[20:23]
	global_load_dwordx4 v[40:43], v[2:3], off offset:1024
	global_load_dwordx4 v[48:51], v[2:3], off offset:1088
	s_waitcnt vmcnt(23)
	ds_bpermute_b32 v52, v134, v52
	ds_bpermute_b32 v53, v134, v53
	ds_bpermute_b32 v54, v134, v54
	ds_bpermute_b32 v55, v134, v55
	ds_bpermute_b32 v60, v134, v60
	ds_bpermute_b32 v61, v134, v61
	ds_bpermute_b32 v62, v134, v62
	ds_bpermute_b32 v63, v134, v63
	s_waitcnt lgkmcnt(0)
	v_mfma_f32_16x16x32_bf16 v[20:23], v[52:55], v[60:63], v[20:23]
	global_load_dwordx4 v[52:55], v[0:1], off offset:1024
	global_load_dwordx4 v[60:63], v[0:1], off offset:1088
	s_waitcnt vmcnt(24)
	ds_bpermute_b32 v56, v134, v56
	ds_bpermute_b32 v57, v134, v57
	ds_bpermute_b32 v58, v134, v58
	ds_bpermute_b32 v59, v134, v59
	ds_bpermute_b32 v64, v134, v64
	ds_bpermute_b32 v65, v134, v65
	ds_bpermute_b32 v66, v134, v66
	ds_bpermute_b32 v67, v134, v67
	s_waitcnt lgkmcnt(0)
	v_mfma_f32_16x16x32_bf16 v[20:23], v[56:59], v[64:67], v[20:23]
	global_load_dwordx4 v[56:59], v[2:3], off offset:1152
	global_load_dwordx4 v[64:67], v[2:3], off offset:1216
	s_waitcnt vmcnt(23)
	ds_bpermute_b32 v68, v134, v68
	ds_bpermute_b32 v69, v134, v69
	ds_bpermute_b32 v70, v134, v70
	ds_bpermute_b32 v71, v134, v71
	ds_bpermute_b32 v76, v134, v76
	ds_bpermute_b32 v77, v134, v77
	ds_bpermute_b32 v78, v134, v78
	ds_bpermute_b32 v79, v134, v79
	s_waitcnt lgkmcnt(0)
	v_mfma_f32_16x16x32_bf16 v[20:23], v[68:71], v[76:79], v[20:23]
	global_load_dwordx4 v[68:71], v[0:1], off offset:1152
	global_load_dwordx4 v[76:79], v[0:1], off offset:1216
	s_waitcnt vmcnt(24)
; template <int MODE> ...
;     ...
;         if (MODE == 0) {
;             const int kb = kh * (K / 2);
;             const bf16_t* ap = A + (size_t)(rt * 16 + fr) * lda + kb + fq * 8;
;             const bf16_t* bp = Bt + (size_t)(ct * 16 + fr) * ldb + kb + fq * 8;
; #pragma unroll 16
;             for (int ks = 0; ks < K / 64; ++ks) {
;                 const bf16x8 af = *(const bf16x8*)(ap + ks * 32), bfv = *(const bf16x8*)(bp + ks * 32);
;                 tot = __builtin_amdgcn_mfma_f32_16x16x32_bf16(bfv, af, tot, 0, 0, 0);
;             }
	ds_bpermute_b32 v72, v134, v72
	ds_bpermute_b32 v73, v134, v73
	ds_bpermute_b32 v74, v134, v74
	ds_bpermute_b32 v75, v134, v75
	ds_bpermute_b32 v80, v134, v80
	ds_bpermute_b32 v81, v134, v81
	ds_bpermute_b32 v82, v134, v82
	ds_bpermute_b32 v83, v134, v83
	s_waitcnt lgkmcnt(0)
	v_mfma_f32_16x16x32_bf16 v[20:23], v[72:75], v[80:83], v[20:23]
	global_load_dwordx4 v[72:75], v[2:3], off offset:1280
	global_load_dwordx4 v[80:83], v[2:3], off offset:1344
	s_waitcnt vmcnt(23)
	ds_bpermute_b32 v84, v134, v84
	ds_bpermute_b32 v85, v134, v85
	ds_bpermute_b32 v86, v134, v86
	ds_bpermute_b32 v87, v134, v87
	ds_bpermute_b32 v92, v134, v92
	ds_bpermute_b32 v93, v134, v93
	ds_bpermute_b32 v94, v134, v94
	ds_bpermute_b32 v95, v134, v95
	s_waitcnt lgkmcnt(0)
	v_mfma_f32_16x16x32_bf16 v[20:23], v[84:87], v[92:95], v[20:23]
	global_load_dwordx4 v[84:87], v[0:1], off offset:1280
	global_load_dwordx4 v[92:95], v[0:1], off offset:1344
	s_waitcnt vmcnt(24)
	ds_bpermute_b32 v88, v134, v88
	ds_bpermute_b32 v89, v134, v89
	ds_bpermute_b32 v90, v134, v90
	ds_bpermute_b32 v91, v134, v91
	ds_bpermute_b32 v96, v134, v96
	ds_bpermute_b32 v97, v134, v97
	ds_bpermute_b32 v98, v134, v98
	ds_bpermute_b32 v99, v134, v99
	s_waitcnt lgkmcnt(0)
	v_mfma_f32_16x16x32_bf16 v[20:23], v[88:91], v[96:99], v[20:23]
	global_load_dwordx4 v[88:91], v[2:3], off offset:1408
	global_load_dwordx4 v[96:99], v[0:1], off offset:1408
	s_waitcnt vmcnt(24)
	ds_bpermute_b32 v100, v134, v100
	ds_bpermute_b32 v101, v134, v101
	ds_bpermute_b32 v102, v134, v102
	ds_bpermute_b32 v103, v134, v103
	ds_bpermute_b32 v104, v134, v104
	ds_bpermute_b32 v105, v134, v105
	ds_bpermute_b32 v106, v134, v106
	ds_bpermute_b32 v107, v134, v107
	s_waitcnt lgkmcnt(0)
	v_mfma_f32_16x16x32_bf16 v[20:23], v[100:103], v[104:107], v[20:23]
	global_load_dwordx4 v[100:103], v[2:3], off offset:1472
	global_load_dwordx4 v[104:107], v[0:1], off offset:1472
	s_waitcnt vmcnt(24)
	ds_bpermute_b32 v108, v134, v108
	ds_bpermute_b32 v109, v134, v109
	ds_bpermute_b32 v110, v134, v110
	ds_bpermute_b32 v111, v134, v111
	ds_bpermute_b32 v112, v134, v112
	ds_bpermute_b32 v113, v134, v113
	ds_bpermute_b32 v114, v134, v114
	ds_bpermute_b32 v115, v134, v115
	s_waitcnt lgkmcnt(0)
	v_mfma_f32_16x16x32_bf16 v[20:23], v[108:111], v[112:115], v[20:23]
	s_waitcnt vmcnt(21)
	ds_bpermute_b32 v116, v134, v116
	ds_bpermute_b32 v117, v134, v117
	ds_bpermute_b32 v118, v134, v118
	ds_bpermute_b32 v119, v134, v119
	ds_bpermute_b32 v24, v134, v24
	ds_bpermute_b32 v25, v134, v25
	ds_bpermute_b32 v26, v134, v26
	ds_bpermute_b32 v27, v134, v27
	s_waitcnt lgkmcnt(0)
	v_mfma_f32_16x16x32_bf16 v[20:23], v[116:119], v[24:27], v[20:23]
	global_load_dwordx4 v[24:27], v[2:3], off offset:1536
	global_load_dwordx4 v[108:111], v[2:3], off offset:1600
	global_load_dwordx4 v[112:115], v[0:1], off offset:1536
	global_load_dwordx4 v[116:119], v[0:1], off offset:1600
	s_waitcnt vmcnt(24)
	ds_bpermute_b32 v120, v134, v120
	ds_bpermute_b32 v121, v134, v121
	ds_bpermute_b32 v122, v134, v122
	ds_bpermute_b32 v123, v134, v123
	ds_bpermute_b32 v124, v134, v124
	ds_bpermute_b32 v125, v134, v125
	ds_bpermute_b32 v126, v134, v126
	ds_bpermute_b32 v127, v134, v127
	s_waitcnt lgkmcnt(0)
	v_mfma_f32_16x16x32_bf16 v[20:23], v[120:123], v[124:127], v[20:23]
	s_waitcnt vmcnt(22)
	ds_bpermute_b32 v28, v134, v28
	ds_bpermute_b32 v29, v134, v29
	ds_bpermute_b32 v30, v134, v30
	ds_bpermute_b32 v31, v134, v31
	ds_bpermute_b32 v32, v134, v32
	ds_bpermute_b32 v33, v134, v33
	ds_bpermute_b32 v34, v134, v34
	ds_bpermute_b32 v35, v134, v35
	s_waitcnt lgkmcnt(0)
	v_mfma_f32_16x16x32_bf16 v[20:23], v[28:31], v[32:35], v[20:23]
	global_load_dwordx4 v[28:31], v[2:3], off offset:1664
	global_load_dwordx4 v[32:35], v[0:1], off offset:1664
	s_waitcnt vmcnt(22)
	ds_bpermute_b32 v36, v134, v36
	ds_bpermute_b32 v37, v134, v37
	ds_bpermute_b32 v38, v134, v38
	ds_bpermute_b32 v39, v134, v39
	ds_bpermute_b32 v44, v134, v44
	ds_bpermute_b32 v45, v134, v45
	ds_bpermute_b32 v46, v134, v46
	ds_bpermute_b32 v47, v134, v47
	s_waitcnt lgkmcnt(0)
	v_mfma_f32_16x16x32_bf16 v[20:23], v[36:39], v[44:47], v[20:23]
	global_load_dwordx4 v[36:39], v[2:3], off offset:1728
	global_load_dwordx4 v[44:47], v[0:1], off offset:1728
	s_waitcnt vmcnt(21)
	ds_bpermute_b32 v40, v134, v40
	ds_bpermute_b32 v41, v134, v41
	ds_bpermute_b32 v42, v134, v42
	ds_bpermute_b32 v43, v134, v43
	ds_bpermute_b32 v52, v134, v52
	ds_bpermute_b32 v53, v134, v53
	ds_bpermute_b32 v54, v134, v54
	ds_bpermute_b32 v55, v134, v55
	s_waitcnt lgkmcnt(0)
	v_mfma_f32_16x16x32_bf16 v[20:23], v[40:43], v[52:55], v[20:23]
	global_load_dwordx4 v[40:43], v[2:3], off offset:1792
	global_load_dwordx4 v[52:55], v[2:3], off offset:1856
	s_waitcnt vmcnt(22)
	ds_bpermute_b32 v48, v134, v48
	ds_bpermute_b32 v49, v134, v49
	ds_bpermute_b32 v50, v134, v50
	ds_bpermute_b32 v51, v134, v51
	ds_bpermute_b32 v60, v134, v60
	ds_bpermute_b32 v61, v134, v61
	ds_bpermute_b32 v62, v134, v62
	ds_bpermute_b32 v63, v134, v63
	s_waitcnt lgkmcnt(0)
	v_mfma_f32_16x16x32_bf16 v[20:23], v[48:51], v[60:63], v[20:23]
	global_load_dwordx4 v[48:51], v[0:1], off offset:1792
	global_load_dwordx4 v[60:63], v[0:1], off offset:1856
	s_waitcnt vmcnt(21)
	ds_bpermute_b32 v56, v134, v56
	ds_bpermute_b32 v57, v134, v57
	ds_bpermute_b32 v58, v134, v58
	ds_bpermute_b32 v59, v134, v59
	ds_bpermute_b32 v68, v134, v68
	ds_bpermute_b32 v69, v134, v69
	ds_bpermute_b32 v70, v134, v70
	ds_bpermute_b32 v71, v134, v71
	s_waitcnt lgkmcnt(0)
	v_mfma_f32_16x16x32_bf16 v[20:23], v[56:59], v[68:71], v[20:23]
	global_load_dwordx4 v[56:59], v[2:3], off offset:1920
	global_load_dwordx4 v[68:71], v[2:3], off offset:1984
	s_waitcnt vmcnt(22)
; template <int MODE> ...
;     ...
;         if (MODE == 0) {
;             const int kb = kh * (K / 2);
;             const bf16_t* ap = A + (size_t)(rt * 16 + fr) * lda + kb + fq * 8;
;             const bf16_t* bp = Bt + (size_t)(ct * 16 + fr) * ldb + kb + fq * 8;
; #pragma unroll 16
;             for (int ks = 0; ks < K / 64; ++ks) {
;                 const bf16x8 af = *(const bf16x8*)(ap + ks * 32), bfv = *(const bf16x8*)(bp + ks * 32);
;                 tot = __builtin_amdgcn_mfma_f32_16x16x32_bf16(bfv, af, tot, 0, 0, 0);
;             }
	ds_bpermute_b32 v64, v134, v64
	ds_bpermute_b32 v65, v134, v65
	ds_bpermute_b32 v66, v134, v66
	ds_bpermute_b32 v67, v134, v67
	ds_bpermute_b32 v76, v134, v76
	ds_bpermute_b32 v77, v134, v77
	ds_bpermute_b32 v78, v134, v78
	ds_bpermute_b32 v79, v134, v79
	s_waitcnt lgkmcnt(0)
	v_mfma_f32_16x16x32_bf16 v[20:23], v[64:67], v[76:79], v[20:23]
	global_load_dwordx4 v[64:67], v[0:1], off offset:1920
	global_load_dwordx4 v[76:79], v[0:1], off offset:1984
	s_waitcnt vmcnt(21)
	ds_bpermute_b32 v72, v134, v72
	ds_bpermute_b32 v73, v134, v73
	ds_bpermute_b32 v74, v134, v74
	ds_bpermute_b32 v75, v134, v75
	ds_bpermute_b32 v84, v134, v84
	ds_bpermute_b32 v85, v134, v85
	ds_bpermute_b32 v86, v134, v86
	ds_bpermute_b32 v87, v134, v87
	s_waitcnt lgkmcnt(0)
	v_mfma_f32_16x16x32_bf16 v[20:23], v[72:75], v[84:87], v[20:23]
	global_load_dwordx4 v[72:75], v[2:3], off offset:2048
	global_load_dwordx4 v[84:87], v[0:1], off offset:2048
	s_waitcnt vmcnt(22)
	ds_bpermute_b32 v80, v134, v80
	ds_bpermute_b32 v81, v134, v81
	ds_bpermute_b32 v82, v134, v82
	ds_bpermute_b32 v83, v134, v83
	ds_bpermute_b32 v92, v134, v92
	ds_bpermute_b32 v93, v134, v93
	ds_bpermute_b32 v94, v134, v94
	ds_bpermute_b32 v95, v134, v95
	s_waitcnt lgkmcnt(0)
	v_mfma_f32_16x16x32_bf16 v[20:23], v[80:83], v[92:95], v[20:23]
	global_load_dwordx4 v[80:83], v[2:3], off offset:2112
	s_waitcnt vmcnt(21)
	ds_bpermute_b32 v88, v134, v88
	ds_bpermute_b32 v89, v134, v89
	ds_bpermute_b32 v90, v134, v90
	ds_bpermute_b32 v91, v134, v91
	ds_bpermute_b32 v96, v134, v96
	ds_bpermute_b32 v97, v134, v97
	ds_bpermute_b32 v98, v134, v98
	ds_bpermute_b32 v99, v134, v99
	s_waitcnt lgkmcnt(0)
	v_mfma_f32_16x16x32_bf16 v[20:23], v[88:91], v[96:99], v[20:23]
	global_load_dwordx4 v[88:91], v[0:1], off offset:2112
	global_load_dwordx4 v[92:95], v[2:3], off offset:2176
	global_load_dwordx4 v[96:99], v[2:3], off offset:2240
	s_waitcnt vmcnt(22)
	ds_bpermute_b32 v100, v134, v100
	ds_bpermute_b32 v101, v134, v101
	ds_bpermute_b32 v102, v134, v102
	ds_bpermute_b32 v103, v134, v103
	ds_bpermute_b32 v104, v134, v104
	ds_bpermute_b32 v105, v134, v105
	ds_bpermute_b32 v106, v134, v106
	ds_bpermute_b32 v107, v134, v107
	s_waitcnt lgkmcnt(0)
	v_mfma_f32_16x16x32_bf16 v[20:23], v[100:103], v[104:107], v[20:23]
	s_waitcnt vmcnt(19)
	ds_bpermute_b32 v24, v134, v24
	ds_bpermute_b32 v25, v134, v25
	ds_bpermute_b32 v26, v134, v26
	ds_bpermute_b32 v27, v134, v27
	ds_bpermute_b32 v112, v134, v112
	ds_bpermute_b32 v113, v134, v113
	ds_bpermute_b32 v114, v134, v114
	ds_bpermute_b32 v115, v134, v115
	s_waitcnt lgkmcnt(0)
	v_mfma_f32_16x16x32_bf16 v[20:23], v[24:27], v[112:115], v[20:23]
	global_load_dwordx4 v[24:27], v[0:1], off offset:2176
	global_load_dwordx4 v[100:103], v[0:1], off offset:2240
	s_waitcnt vmcnt(20)
	ds_bpermute_b32 v108, v134, v108
	ds_bpermute_b32 v109, v134, v109
	ds_bpermute_b32 v110, v134, v110
	ds_bpermute_b32 v111, v134, v111
	ds_bpermute_b32 v116, v134, v116
	ds_bpermute_b32 v117, v134, v117
	ds_bpermute_b32 v118, v134, v118
	ds_bpermute_b32 v119, v134, v119
	s_waitcnt lgkmcnt(0)
	v_mfma_f32_16x16x32_bf16 v[20:23], v[108:111], v[116:119], v[20:23]
	global_load_dwordx4 v[104:107], v[2:3], off offset:2304
	global_load_dwordx4 v[108:111], v[0:1], off offset:2304
	s_waitcnt vmcnt(20)
	ds_bpermute_b32 v28, v134, v28
	ds_bpermute_b32 v29, v134, v29
	ds_bpermute_b32 v30, v134, v30
	ds_bpermute_b32 v31, v134, v31
	ds_bpermute_b32 v32, v134, v32
	ds_bpermute_b32 v33, v134, v33
	ds_bpermute_b32 v34, v134, v34
	ds_bpermute_b32 v35, v134, v35
	s_waitcnt lgkmcnt(0)
	v_mfma_f32_16x16x32_bf16 v[20:23], v[28:31], v[32:35], v[20:23]
	global_load_dwordx4 v[28:31], v[2:3], off offset:2368
	global_load_dwordx4 v[32:35], v[0:1], off offset:2368
	s_waitcnt vmcnt(20)
	ds_bpermute_b32 v36, v134, v36
	ds_bpermute_b32 v37, v134, v37
	ds_bpermute_b32 v38, v134, v38
	ds_bpermute_b32 v39, v134, v39
	ds_bpermute_b32 v44, v134, v44
	ds_bpermute_b32 v45, v134, v45
	ds_bpermute_b32 v46, v134, v46
	ds_bpermute_b32 v47, v134, v47
	s_waitcnt lgkmcnt(0)
	v_mfma_f32_16x16x32_bf16 v[20:23], v[36:39], v[44:47], v[20:23]
	global_load_dwordx4 v[36:39], v[2:3], off offset:2432
	global_load_dwordx4 v[44:47], v[2:3], off offset:2496
	s_waitcnt vmcnt(19)
	ds_bpermute_b32 v40, v134, v40
	ds_bpermute_b32 v41, v134, v41
	ds_bpermute_b32 v42, v134, v42
	ds_bpermute_b32 v43, v134, v43
	ds_bpermute_b32 v48, v134, v48
	ds_bpermute_b32 v49, v134, v49
	ds_bpermute_b32 v50, v134, v50
	ds_bpermute_b32 v51, v134, v51
	s_waitcnt lgkmcnt(0)
	v_mfma_f32_16x16x32_bf16 v[20:23], v[40:43], v[48:51], v[20:23]
	global_load_dwordx4 v[40:43], v[0:1], off offset:2432
	global_load_dwordx4 v[48:51], v[0:1], off offset:2496
	s_waitcnt vmcnt(20)
	ds_bpermute_b32 v52, v134, v52
	ds_bpermute_b32 v53, v134, v53
	ds_bpermute_b32 v54, v134, v54
	ds_bpermute_b32 v55, v134, v55
	ds_bpermute_b32 v60, v134, v60
	ds_bpermute_b32 v61, v134, v61
	ds_bpermute_b32 v62, v134, v62
	ds_bpermute_b32 v63, v134, v63
	s_waitcnt lgkmcnt(0)
	v_mfma_f32_16x16x32_bf16 v[20:23], v[52:55], v[60:63], v[20:23]
	global_load_dwordx4 v[52:55], v[2:3], off offset:2560
	global_load_dwordx4 v[60:63], v[2:3], off offset:2624
	s_waitcnt vmcnt(19)
	ds_bpermute_b32 v56, v134, v56
	ds_bpermute_b32 v57, v134, v57
	ds_bpermute_b32 v58, v134, v58
	ds_bpermute_b32 v59, v134, v59
	ds_bpermute_b32 v64, v134, v64
	ds_bpermute_b32 v65, v134, v65
	ds_bpermute_b32 v66, v134, v66
	ds_bpermute_b32 v67, v134, v67
	s_waitcnt lgkmcnt(0)
	v_mfma_f32_16x16x32_bf16 v[20:23], v[56:59], v[64:67], v[20:23]
	global_load_dwordx4 v[56:59], v[0:1], off offset:2560
	global_load_dwordx4 v[64:67], v[0:1], off offset:2624
	s_waitcnt vmcnt(20)
; template <int MODE> ...
;     ...
;         if (MODE == 0) {
;             const int kb = kh * (K / 2);
;             const bf16_t* ap = A + (size_t)(rt * 16 + fr) * lda + kb + fq * 8;
;             const bf16_t* bp = Bt + (size_t)(ct * 16 + fr) * ldb + kb + fq * 8;
; #pragma unroll 16
;             for (int ks = 0; ks < K / 64; ++ks) {
;                 const bf16x8 af = *(const bf16x8*)(ap + ks * 32), bfv = *(const bf16x8*)(bp + ks * 32);
;                 tot = __builtin_amdgcn_mfma_f32_16x16x32_bf16(bfv, af, tot, 0, 0, 0);
;             }
	ds_bpermute_b32 v68, v134, v68
	ds_bpermute_b32 v69, v134, v69
	ds_bpermute_b32 v70, v134, v70
	ds_bpermute_b32 v71, v134, v71
	ds_bpermute_b32 v76, v134, v76
	ds_bpermute_b32 v77, v134, v77
	ds_bpermute_b32 v78, v134, v78
	ds_bpermute_b32 v79, v134, v79
	s_waitcnt lgkmcnt(0)
	v_mfma_f32_16x16x32_bf16 v[20:23], v[68:71], v[76:79], v[20:23]
	global_load_dwordx4 v[68:71], v[2:3], off offset:2688
	global_load_dwordx4 v[76:79], v[0:1], off offset:2688
	s_waitcnt vmcnt(20)
	ds_bpermute_b32 v72, v134, v72
	ds_bpermute_b32 v73, v134, v73
	ds_bpermute_b32 v74, v134, v74
	ds_bpermute_b32 v75, v134, v75
	ds_bpermute_b32 v84, v134, v84
	ds_bpermute_b32 v85, v134, v85
	ds_bpermute_b32 v86, v134, v86
	ds_bpermute_b32 v87, v134, v87
	s_waitcnt lgkmcnt(0)
	v_mfma_f32_16x16x32_bf16 v[20:23], v[72:75], v[84:87], v[20:23]
	global_load_dwordx4 v[72:75], v[2:3], off offset:2752
	s_waitcnt vmcnt(19)
	ds_bpermute_b32 v80, v134, v80
	ds_bpermute_b32 v81, v134, v81
	ds_bpermute_b32 v82, v134, v82
	ds_bpermute_b32 v83, v134, v83
	ds_bpermute_b32 v88, v134, v88
	ds_bpermute_b32 v89, v134, v89
	ds_bpermute_b32 v90, v134, v90
	ds_bpermute_b32 v91, v134, v91
	s_waitcnt lgkmcnt(0)
	v_mfma_f32_16x16x32_bf16 v[20:23], v[80:83], v[88:91], v[20:23]
	global_load_dwordx4 v[80:83], v[0:1], off offset:2752
	s_waitcnt vmcnt(17)
	ds_bpermute_b32 v92, v134, v92
	ds_bpermute_b32 v93, v134, v93
	ds_bpermute_b32 v94, v134, v94
	ds_bpermute_b32 v95, v134, v95
	ds_bpermute_b32 v24, v134, v24
	ds_bpermute_b32 v25, v134, v25
	ds_bpermute_b32 v26, v134, v26
	ds_bpermute_b32 v27, v134, v27
	s_waitcnt lgkmcnt(0)
	v_mfma_f32_16x16x32_bf16 v[20:23], v[92:95], v[24:27], v[20:23]
	global_load_dwordx4 v[24:27], v[2:3], off offset:2816
	global_load_dwordx4 v[84:87], v[2:3], off offset:2880
	global_load_dwordx4 v[88:91], v[0:1], off offset:2816
	global_load_dwordx4 v[92:95], v[0:1], off offset:2880
	s_waitcnt vmcnt(20)
	ds_bpermute_b32 v96, v134, v96
	ds_bpermute_b32 v97, v134, v97
	ds_bpermute_b32 v98, v134, v98
	ds_bpermute_b32 v99, v134, v99
	ds_bpermute_b32 v100, v134, v100
	ds_bpermute_b32 v101, v134, v101
	ds_bpermute_b32 v102, v134, v102
	ds_bpermute_b32 v103, v134, v103
	s_waitcnt lgkmcnt(0)
	v_mfma_f32_16x16x32_bf16 v[20:23], v[96:99], v[100:103], v[20:23]
	global_load_dwordx4 v[96:99], v[2:3], off offset:2944
	global_load_dwordx4 v[100:103], v[0:1], off offset:2944
	s_waitcnt vmcnt(20)
	ds_bpermute_b32 v104, v134, v104
	ds_bpermute_b32 v105, v134, v105
	ds_bpermute_b32 v106, v134, v106
	ds_bpermute_b32 v107, v134, v107
	ds_bpermute_b32 v108, v134, v108
	ds_bpermute_b32 v109, v134, v109
	ds_bpermute_b32 v110, v134, v110
	ds_bpermute_b32 v111, v134, v111
	s_waitcnt lgkmcnt(0)
	v_mfma_f32_16x16x32_bf16 v[20:23], v[104:107], v[108:111], v[20:23]
	s_waitcnt vmcnt(18)
	ds_bpermute_b32 v28, v134, v28
	ds_bpermute_b32 v29, v134, v29
	ds_bpermute_b32 v30, v134, v30
	ds_bpermute_b32 v31, v134, v31
	ds_bpermute_b32 v32, v134, v32
	ds_bpermute_b32 v33, v134, v33
	ds_bpermute_b32 v34, v134, v34
	ds_bpermute_b32 v35, v134, v35
	s_waitcnt lgkmcnt(0)
	v_mfma_f32_16x16x32_bf16 v[20:23], v[28:31], v[32:35], v[20:23]
	global_load_dwordx4 v[28:31], v[2:3], off offset:3008
	global_load_dwordx4 v[32:35], v[0:1], off offset:3008
	s_waitcnt vmcnt(17)
	ds_bpermute_b32 v36, v134, v36
	ds_bpermute_b32 v37, v134, v37
	ds_bpermute_b32 v38, v134, v38
	ds_bpermute_b32 v39, v134, v39
	ds_bpermute_b32 v40, v134, v40
	ds_bpermute_b32 v41, v134, v41
	ds_bpermute_b32 v42, v134, v42
	ds_bpermute_b32 v43, v134, v43
	s_waitcnt lgkmcnt(0)
	v_mfma_f32_16x16x32_bf16 v[20:23], v[36:39], v[40:43], v[20:23]
	global_load_dwordx4 v[36:39], v[2:3], off offset:3072
	global_load_dwordx4 v[40:43], v[2:3], off offset:3136
	s_waitcnt vmcnt(18)
	ds_bpermute_b32 v44, v134, v44
	ds_bpermute_b32 v45, v134, v45
	ds_bpermute_b32 v46, v134, v46
	ds_bpermute_b32 v47, v134, v47
	ds_bpermute_b32 v48, v134, v48
	ds_bpermute_b32 v49, v134, v49
	ds_bpermute_b32 v50, v134, v50
	ds_bpermute_b32 v51, v134, v51
	s_waitcnt lgkmcnt(0)
	v_mfma_f32_16x16x32_bf16 v[20:23], v[44:47], v[48:51], v[20:23]
	global_load_dwordx4 v[44:47], v[0:1], off offset:3072
	global_load_dwordx4 v[48:51], v[0:1], off offset:3136
	s_waitcnt vmcnt(17)
	ds_bpermute_b32 v52, v134, v52
	ds_bpermute_b32 v53, v134, v53
	ds_bpermute_b32 v54, v134, v54
	ds_bpermute_b32 v55, v134, v55
	ds_bpermute_b32 v56, v134, v56
	ds_bpermute_b32 v57, v134, v57
	ds_bpermute_b32 v58, v134, v58
	ds_bpermute_b32 v59, v134, v59
	s_waitcnt lgkmcnt(0)
	v_mfma_f32_16x16x32_bf16 v[20:23], v[52:55], v[56:59], v[20:23]
	global_load_dwordx4 v[52:55], v[2:3], off offset:3200
	global_load_dwordx4 v[56:59], v[2:3], off offset:3264
	s_waitcnt vmcnt(18)
	ds_bpermute_b32 v60, v134, v60
	ds_bpermute_b32 v61, v134, v61
	ds_bpermute_b32 v62, v134, v62
	ds_bpermute_b32 v63, v134, v63
	ds_bpermute_b32 v64, v134, v64
	ds_bpermute_b32 v65, v134, v65
	ds_bpermute_b32 v66, v134, v66
	ds_bpermute_b32 v67, v134, v67
	s_waitcnt lgkmcnt(0)
	v_mfma_f32_16x16x32_bf16 v[20:23], v[60:63], v[64:67], v[20:23]
	global_load_dwordx4 v[60:63], v[0:1], off offset:3200
	global_load_dwordx4 v[64:67], v[0:1], off offset:3264
	s_waitcnt vmcnt(18)
	ds_bpermute_b32 v68, v134, v68
	ds_bpermute_b32 v69, v134, v69
	ds_bpermute_b32 v70, v134, v70
	ds_bpermute_b32 v71, v134, v71
	ds_bpermute_b32 v76, v134, v76
	ds_bpermute_b32 v77, v134, v77
	ds_bpermute_b32 v78, v134, v78
	ds_bpermute_b32 v79, v134, v79
	s_waitcnt lgkmcnt(0)
	v_mfma_f32_16x16x32_bf16 v[20:23], v[68:71], v[76:79], v[20:23]
	global_load_dwordx4 v[68:71], v[2:3], off offset:3328
	s_waitcnt vmcnt(17)
; template <int MODE> ...
;     ...
;         if (MODE == 0) {
;             const int kb = kh * (K / 2);
;             const bf16_t* ap = A + (size_t)(rt * 16 + fr) * lda + kb + fq * 8;
;             const bf16_t* bp = Bt + (size_t)(ct * 16 + fr) * ldb + kb + fq * 8;
; #pragma unroll 16
;             for (int ks = 0; ks < K / 64; ++ks) {
;                 const bf16x8 af = *(const bf16x8*)(ap + ks * 32), bfv = *(const bf16x8*)(bp + ks * 32);
;                 tot = __builtin_amdgcn_mfma_f32_16x16x32_bf16(bfv, af, tot, 0, 0, 0);
;             }
	ds_bpermute_b32 v72, v134, v72
	ds_bpermute_b32 v73, v134, v73
	ds_bpermute_b32 v74, v134, v74
	ds_bpermute_b32 v75, v134, v75
	ds_bpermute_b32 v80, v134, v80
	ds_bpermute_b32 v81, v134, v81
	ds_bpermute_b32 v82, v134, v82
	ds_bpermute_b32 v83, v134, v83
	s_waitcnt lgkmcnt(0)
	v_mfma_f32_16x16x32_bf16 v[20:23], v[72:75], v[80:83], v[20:23]
	global_load_dwordx4 v[72:75], v[0:1], off offset:3328
	s_waitcnt vmcnt(15)
	ds_bpermute_b32 v24, v134, v24
	ds_bpermute_b32 v25, v134, v25
	ds_bpermute_b32 v26, v134, v26
	ds_bpermute_b32 v27, v134, v27
	ds_bpermute_b32 v88, v134, v88
	ds_bpermute_b32 v89, v134, v89
	ds_bpermute_b32 v90, v134, v90
	ds_bpermute_b32 v91, v134, v91
	s_waitcnt lgkmcnt(0)
	v_mfma_f32_16x16x32_bf16 v[20:23], v[24:27], v[88:91], v[20:23]
	global_load_dwordx4 v[24:27], v[2:3], off offset:3392
	global_load_dwordx4 v[76:79], v[0:1], off offset:3392
	s_waitcnt vmcnt(16)
	ds_bpermute_b32 v84, v134, v84
	ds_bpermute_b32 v85, v134, v85
	ds_bpermute_b32 v86, v134, v86
	ds_bpermute_b32 v87, v134, v87
	ds_bpermute_b32 v92, v134, v92
	ds_bpermute_b32 v93, v134, v93
	ds_bpermute_b32 v94, v134, v94
	ds_bpermute_b32 v95, v134, v95
	s_waitcnt lgkmcnt(0)
	v_mfma_f32_16x16x32_bf16 v[20:23], v[84:87], v[92:95], v[20:23]
	global_load_dwordx4 v[80:83], v[2:3], off offset:3456
	global_load_dwordx4 v[84:87], v[2:3], off offset:3520
	global_load_dwordx4 v[88:91], v[0:1], off offset:3456
	global_load_dwordx4 v[92:95], v[0:1], off offset:3520
	s_waitcnt vmcnt(18)
	ds_bpermute_b32 v96, v134, v96
	ds_bpermute_b32 v97, v134, v97
	ds_bpermute_b32 v98, v134, v98
	ds_bpermute_b32 v99, v134, v99
	ds_bpermute_b32 v100, v134, v100
	ds_bpermute_b32 v101, v134, v101
	ds_bpermute_b32 v102, v134, v102
	ds_bpermute_b32 v103, v134, v103
	s_waitcnt lgkmcnt(0)
	v_mfma_f32_16x16x32_bf16 v[20:23], v[96:99], v[100:103], v[20:23]
	s_waitcnt vmcnt(16)
	ds_bpermute_b32 v28, v134, v28
	ds_bpermute_b32 v29, v134, v29
	ds_bpermute_b32 v30, v134, v30
	ds_bpermute_b32 v31, v134, v31
	ds_bpermute_b32 v32, v134, v32
	ds_bpermute_b32 v33, v134, v33
	ds_bpermute_b32 v34, v134, v34
	ds_bpermute_b32 v35, v134, v35
	s_waitcnt lgkmcnt(0)
	v_mfma_f32_16x16x32_bf16 v[20:23], v[28:31], v[32:35], v[20:23]
	global_load_dwordx4 v[28:31], v[2:3], off offset:3584
	global_load_dwordx4 v[32:35], v[0:1], off offset:3584
	s_waitcnt vmcnt(15)
	ds_bpermute_b32 v36, v134, v36
	ds_bpermute_b32 v37, v134, v37
	ds_bpermute_b32 v38, v134, v38
	ds_bpermute_b32 v39, v134, v39
	ds_bpermute_b32 v44, v134, v44
	ds_bpermute_b32 v45, v134, v45
	ds_bpermute_b32 v46, v134, v46
	ds_bpermute_b32 v47, v134, v47
	s_waitcnt lgkmcnt(0)
	v_mfma_f32_16x16x32_bf16 v[20:23], v[36:39], v[44:47], v[20:23]
	global_load_dwordx4 v[36:39], v[2:3], off offset:3648
	global_load_dwordx4 v[44:47], v[0:1], off offset:3648
	s_waitcnt vmcnt(16)
	ds_bpermute_b32 v40, v134, v40
	ds_bpermute_b32 v41, v134, v41
	ds_bpermute_b32 v42, v134, v42
	ds_bpermute_b32 v43, v134, v43
	ds_bpermute_b32 v48, v134, v48
	ds_bpermute_b32 v49, v134, v49
	ds_bpermute_b32 v50, v134, v50
	ds_bpermute_b32 v51, v134, v51
	s_waitcnt lgkmcnt(0)
	v_mfma_f32_16x16x32_bf16 v[20:23], v[40:43], v[48:51], v[20:23]
	global_load_dwordx4 v[40:43], v[2:3], off offset:3712
	global_load_dwordx4 v[48:51], v[2:3], off offset:3776
	s_waitcnt vmcnt(15)
	ds_bpermute_b32 v52, v134, v52
	ds_bpermute_b32 v53, v134, v53
	ds_bpermute_b32 v54, v134, v54
	ds_bpermute_b32 v55, v134, v55
	ds_bpermute_b32 v60, v134, v60
	ds_bpermute_b32 v61, v134, v61
	ds_bpermute_b32 v62, v134, v62
	ds_bpermute_b32 v63, v134, v63
	s_waitcnt lgkmcnt(0)
	v_mfma_f32_16x16x32_bf16 v[20:23], v[52:55], v[60:63], v[20:23]
	global_load_dwordx4 v[52:55], v[0:1], off offset:3712
	global_load_dwordx4 v[60:63], v[0:1], off offset:3776
	s_waitcnt vmcnt(16)
	ds_bpermute_b32 v56, v134, v56
	ds_bpermute_b32 v57, v134, v57
	ds_bpermute_b32 v58, v134, v58
	ds_bpermute_b32 v59, v134, v59
	ds_bpermute_b32 v64, v134, v64
	ds_bpermute_b32 v65, v134, v65
	ds_bpermute_b32 v66, v134, v66
	ds_bpermute_b32 v67, v134, v67
	s_waitcnt lgkmcnt(0)
	v_mfma_f32_16x16x32_bf16 v[20:23], v[56:59], v[64:67], v[20:23]
	global_load_dwordx4 v[56:59], v[2:3], off offset:3840
	global_load_dwordx4 v[64:67], v[0:1], off offset:3840
	s_waitcnt vmcnt(16)
	ds_bpermute_b32 v68, v134, v68
	ds_bpermute_b32 v69, v134, v69
	ds_bpermute_b32 v70, v134, v70
	ds_bpermute_b32 v71, v134, v71
	ds_bpermute_b32 v72, v134, v72
	ds_bpermute_b32 v73, v134, v73
	ds_bpermute_b32 v74, v134, v74
	ds_bpermute_b32 v75, v134, v75
	s_waitcnt lgkmcnt(0)
	v_mfma_f32_16x16x32_bf16 v[20:23], v[68:71], v[72:75], v[20:23]
	s_waitcnt vmcnt(14)
	ds_bpermute_b32 v24, v134, v24
	ds_bpermute_b32 v25, v134, v25
	ds_bpermute_b32 v26, v134, v26
	ds_bpermute_b32 v27, v134, v27
	ds_bpermute_b32 v76, v134, v76
	ds_bpermute_b32 v77, v134, v77
	ds_bpermute_b32 v78, v134, v78
	ds_bpermute_b32 v79, v134, v79
	s_waitcnt lgkmcnt(0)
	v_mfma_f32_16x16x32_bf16 v[20:23], v[24:27], v[76:79], v[20:23]
	global_load_dwordx4 v[24:27], v[0:1], off offset:3904
	global_load_dwordx4 v[68:71], v[0:1], off offset:3968
	global_load_dwordx4 v[72:75], v[0:1], off offset:4032
	s_waitcnt vmcnt(14)
	ds_bpermute_b32 v80, v134, v80
	ds_bpermute_b32 v81, v134, v81
	ds_bpermute_b32 v82, v134, v82
	ds_bpermute_b32 v83, v134, v83
	ds_bpermute_b32 v88, v134, v88
	ds_bpermute_b32 v89, v134, v89
	ds_bpermute_b32 v90, v134, v90
	ds_bpermute_b32 v91, v134, v91
	s_waitcnt lgkmcnt(0)
	v_mfma_f32_16x16x32_bf16 v[20:23], v[80:83], v[88:91], v[20:23]
	global_load_dwordx4 v[76:79], v[2:3], off offset:3904
	global_load_dwordx4 v[80:83], v[2:3], off offset:3968
	global_load_dwordx4 v[88:91], v[2:3], off offset:4032
	s_waitcnt vmcnt(16)
; template <int MODE> ...
;     ...
;         if (MODE == 0) {
;             const int kb = kh * (K / 2);
;             const bf16_t* ap = A + (size_t)(rt * 16 + fr) * lda + kb + fq * 8;
;             const bf16_t* bp = Bt + (size_t)(ct * 16 + fr) * ldb + kb + fq * 8;
; #pragma unroll 16
;             for (int ks = 0; ks < K / 64; ++ks) {
;                 const bf16x8 af = *(const bf16x8*)(ap + ks * 32), bfv = *(const bf16x8*)(bp + ks * 32);
;                 tot = __builtin_amdgcn_mfma_f32_16x16x32_bf16(bfv, af, tot, 0, 0, 0);
;             }
	ds_bpermute_b32 v84, v134, v84
	ds_bpermute_b32 v85, v134, v85
	ds_bpermute_b32 v86, v134, v86
	ds_bpermute_b32 v87, v134, v87
	ds_bpermute_b32 v92, v134, v92
	ds_bpermute_b32 v93, v134, v93
	ds_bpermute_b32 v94, v134, v94
	ds_bpermute_b32 v95, v134, v95
	s_waitcnt lgkmcnt(0)
	v_mfma_f32_16x16x32_bf16 v[20:23], v[84:87], v[92:95], v[20:23]
	v_add_co_u32_e32 v92, vcc, s18, v2
	s_nop 1
	v_addc_co_u32_e32 v93, vcc, 0, v3, vcc
	global_load_dwordx4 v[84:87], v[92:93], off
	v_add_co_u32_e32 v94, vcc, s18, v0
	s_waitcnt vmcnt(15)
	ds_bpermute_b32 v28, v134, v28
	ds_bpermute_b32 v29, v134, v29
	ds_bpermute_b32 v30, v134, v30
	ds_bpermute_b32 v31, v134, v31
	ds_bpermute_b32 v32, v134, v32
	ds_bpermute_b32 v33, v134, v33
	ds_bpermute_b32 v34, v134, v34
	ds_bpermute_b32 v35, v134, v35
	s_waitcnt lgkmcnt(0)
	v_mfma_f32_16x16x32_bf16 v[20:23], v[28:31], v[32:35], v[20:23]
	v_addc_co_u32_e32 v95, vcc, 0, v1, vcc
	global_load_dwordx4 v[0:3], v[92:93], off offset:64
	global_load_dwordx4 v[28:31], v[94:95], off
	global_load_dwordx4 v[32:35], v[94:95], off offset:64
	s_waitcnt vmcnt(16)
	ds_bpermute_b32 v36, v134, v36
	ds_bpermute_b32 v37, v134, v37
	ds_bpermute_b32 v38, v134, v38
	ds_bpermute_b32 v39, v134, v39
	ds_bpermute_b32 v44, v134, v44
	ds_bpermute_b32 v45, v134, v45
	ds_bpermute_b32 v46, v134, v46
	ds_bpermute_b32 v47, v134, v47
	s_waitcnt lgkmcnt(0)
	v_mfma_f32_16x16x32_bf16 v[20:23], v[36:39], v[44:47], v[20:23]
	s_and_b64 vcc, exec, s[4:5]
	s_waitcnt vmcnt(13)
	ds_bpermute_b32 v40, v134, v40
	ds_bpermute_b32 v41, v134, v41
	ds_bpermute_b32 v42, v134, v42
	ds_bpermute_b32 v43, v134, v43
	ds_bpermute_b32 v52, v134, v52
	ds_bpermute_b32 v53, v134, v53
	ds_bpermute_b32 v54, v134, v54
	ds_bpermute_b32 v55, v134, v55
	s_waitcnt lgkmcnt(0)
	v_mfma_f32_16x16x32_bf16 v[20:23], v[40:43], v[52:55], v[20:23]
	global_load_dwordx4 v[36:39], v[92:93], off offset:128
	global_load_dwordx4 v[40:43], v[94:95], off offset:128
	global_load_dwordx4 v[44:47], v[92:93], off offset:192
	s_waitcnt vmcnt(15)
	ds_bpermute_b32 v48, v134, v48
	ds_bpermute_b32 v49, v134, v49
	ds_bpermute_b32 v50, v134, v50
	ds_bpermute_b32 v51, v134, v51
	ds_bpermute_b32 v60, v134, v60
	ds_bpermute_b32 v61, v134, v61
	ds_bpermute_b32 v62, v134, v62
	ds_bpermute_b32 v63, v134, v63
	s_waitcnt lgkmcnt(0)
	v_mfma_f32_16x16x32_bf16 v[20:23], v[48:51], v[60:63], v[20:23]
	global_load_dwordx4 v[48:51], v[94:95], off offset:192
	s_waitcnt vmcnt(14)
	ds_bpermute_b32 v56, v134, v56
	ds_bpermute_b32 v57, v134, v57
	ds_bpermute_b32 v58, v134, v58
	ds_bpermute_b32 v59, v134, v59
	ds_bpermute_b32 v64, v134, v64
	ds_bpermute_b32 v65, v134, v65
	ds_bpermute_b32 v66, v134, v66
	ds_bpermute_b32 v67, v134, v67
	s_waitcnt lgkmcnt(0)
	v_mfma_f32_16x16x32_bf16 v[20:23], v[56:59], v[64:67], v[20:23]
	s_waitcnt vmcnt(10)
	ds_bpermute_b32 v76, v134, v76
	ds_bpermute_b32 v77, v134, v77
	ds_bpermute_b32 v78, v134, v78
	ds_bpermute_b32 v79, v134, v79
	ds_bpermute_b32 v24, v134, v24
	ds_bpermute_b32 v25, v134, v25
	ds_bpermute_b32 v26, v134, v26
	ds_bpermute_b32 v27, v134, v27
	s_waitcnt lgkmcnt(0)
	v_mfma_f32_16x16x32_bf16 v[20:23], v[76:79], v[24:27], v[20:23]
	global_load_dwordx4 v[24:27], v[92:93], off offset:256
	global_load_dwordx4 v[52:55], v[92:93], off offset:320
	global_load_dwordx4 v[56:59], v[94:95], off offset:256
	global_load_dwordx4 v[60:63], v[94:95], off offset:320
	s_waitcnt vmcnt(13)
	ds_bpermute_b32 v80, v134, v80
	ds_bpermute_b32 v81, v134, v81
	ds_bpermute_b32 v82, v134, v82
	ds_bpermute_b32 v83, v134, v83
	ds_bpermute_b32 v68, v134, v68
	ds_bpermute_b32 v69, v134, v69
	ds_bpermute_b32 v70, v134, v70
	ds_bpermute_b32 v71, v134, v71
	s_waitcnt lgkmcnt(0)
	v_mfma_f32_16x16x32_bf16 v[20:23], v[80:83], v[68:71], v[20:23]
	global_load_dwordx4 v[64:67], v[92:93], off offset:384
	global_load_dwordx4 v[68:71], v[92:93], off offset:448
	s_waitcnt vmcnt(14)
	ds_bpermute_b32 v88, v134, v88
	ds_bpermute_b32 v89, v134, v89
	ds_bpermute_b32 v90, v134, v90
	ds_bpermute_b32 v91, v134, v91
	ds_bpermute_b32 v72, v134, v72
	ds_bpermute_b32 v73, v134, v73
	ds_bpermute_b32 v74, v134, v74
	ds_bpermute_b32 v75, v134, v75
	s_waitcnt lgkmcnt(0)
	v_mfma_f32_16x16x32_bf16 v[20:23], v[88:91], v[72:75], v[20:23]
	s_waitcnt vmcnt(11)
	ds_bpermute_b32 v84, v134, v84
	ds_bpermute_b32 v85, v134, v85
	ds_bpermute_b32 v86, v134, v86
	ds_bpermute_b32 v87, v134, v87
	ds_bpermute_b32 v28, v134, v28
	ds_bpermute_b32 v29, v134, v29
	ds_bpermute_b32 v30, v134, v30
	ds_bpermute_b32 v31, v134, v31
	s_waitcnt lgkmcnt(0)
	v_mfma_f32_16x16x32_bf16 v[20:23], v[84:87], v[28:31], v[20:23]
	global_load_dwordx4 v[28:31], v[94:95], off offset:384
	global_load_dwordx4 v[72:75], v[94:95], off offset:448
	s_waitcnt vmcnt(12)
	ds_bpermute_b32 v0, v134, v0
	ds_bpermute_b32 v1, v134, v1
	ds_bpermute_b32 v2, v134, v2
	ds_bpermute_b32 v3, v134, v3
	ds_bpermute_b32 v32, v134, v32
	ds_bpermute_b32 v33, v134, v33
	ds_bpermute_b32 v34, v134, v34
	ds_bpermute_b32 v35, v134, v35
	s_waitcnt lgkmcnt(0)
	v_mfma_f32_16x16x32_bf16 v[0:3], v[0:3], v[32:35], v[20:23]
	s_nop 3
	global_load_dwordx4 v[20:23], v[92:93], off offset:512
	global_load_dwordx4 v[32:35], v[94:95], off offset:512
	s_waitcnt vmcnt(12)
	ds_bpermute_b32 v36, v134, v36
	ds_bpermute_b32 v37, v134, v37
	ds_bpermute_b32 v38, v134, v38
	ds_bpermute_b32 v39, v134, v39
	ds_bpermute_b32 v40, v134, v40
	ds_bpermute_b32 v41, v134, v41
	ds_bpermute_b32 v42, v134, v42
	ds_bpermute_b32 v43, v134, v43
	s_waitcnt lgkmcnt(0)
	v_mfma_f32_16x16x32_bf16 v[0:3], v[36:39], v[40:43], v[0:3]
	global_load_dwordx4 v[36:39], v[92:93], off offset:576
	global_load_dwordx4 v[40:43], v[94:95], off offset:576
	s_waitcnt vmcnt(12)
; template <int MODE> ...
;     ...
;         if (MODE == 0) {
;             const int kb = kh * (K / 2);
;             const bf16_t* ap = A + (size_t)(rt * 16 + fr) * lda + kb + fq * 8;
;             const bf16_t* bp = Bt + (size_t)(ct * 16 + fr) * ldb + kb + fq * 8;
; #pragma unroll 16
;             for (int ks = 0; ks < K / 64; ++ks) {
;                 const bf16x8 af = *(const bf16x8*)(ap + ks * 32), bfv = *(const bf16x8*)(bp + ks * 32);
;                 tot = __builtin_amdgcn_mfma_f32_16x16x32_bf16(bfv, af, tot, 0, 0, 0);
;             }
	ds_bpermute_b32 v44, v134, v44
	ds_bpermute_b32 v45, v134, v45
	ds_bpermute_b32 v46, v134, v46
	ds_bpermute_b32 v47, v134, v47
	ds_bpermute_b32 v48, v134, v48
	ds_bpermute_b32 v49, v134, v49
	ds_bpermute_b32 v50, v134, v50
	ds_bpermute_b32 v51, v134, v51
	s_waitcnt lgkmcnt(0)
	v_mfma_f32_16x16x32_bf16 v[0:3], v[44:47], v[48:51], v[0:3]
	s_waitcnt vmcnt(9)
	ds_bpermute_b32 v24, v134, v24
	ds_bpermute_b32 v25, v134, v25
	ds_bpermute_b32 v26, v134, v26
	ds_bpermute_b32 v27, v134, v27
	ds_bpermute_b32 v56, v134, v56
	ds_bpermute_b32 v57, v134, v57
	ds_bpermute_b32 v58, v134, v58
	ds_bpermute_b32 v59, v134, v59
	s_waitcnt lgkmcnt(0)
	v_mfma_f32_16x16x32_bf16 v[0:3], v[24:27], v[56:59], v[0:3]
	global_load_dwordx4 v[24:27], v[92:93], off offset:640
	global_load_dwordx4 v[44:47], v[92:93], off offset:704
	s_waitcnt vmcnt(10)
	ds_bpermute_b32 v52, v134, v52
	ds_bpermute_b32 v53, v134, v53
	ds_bpermute_b32 v54, v134, v54
	ds_bpermute_b32 v55, v134, v55
	ds_bpermute_b32 v60, v134, v60
	ds_bpermute_b32 v61, v134, v61
	ds_bpermute_b32 v62, v134, v62
	ds_bpermute_b32 v63, v134, v63
	s_waitcnt lgkmcnt(0)
	v_mfma_f32_16x16x32_bf16 v[0:3], v[52:55], v[60:63], v[0:3]
	global_load_dwordx4 v[48:51], v[94:95], off offset:640
	global_load_dwordx4 v[52:55], v[94:95], off offset:704
	s_waitcnt vmcnt(9)
	ds_bpermute_b32 v64, v134, v64
	ds_bpermute_b32 v65, v134, v65
	ds_bpermute_b32 v66, v134, v66
	ds_bpermute_b32 v67, v134, v67
	ds_bpermute_b32 v28, v134, v28
	ds_bpermute_b32 v29, v134, v29
	ds_bpermute_b32 v30, v134, v30
	ds_bpermute_b32 v31, v134, v31
	s_waitcnt lgkmcnt(0)
	v_mfma_f32_16x16x32_bf16 v[0:3], v[64:67], v[28:31], v[0:3]
	global_load_dwordx4 v[28:31], v[92:93], off offset:768
	global_load_dwordx4 v[56:59], v[92:93], off offset:832
	global_load_dwordx4 v[60:63], v[94:95], off offset:768
	global_load_dwordx4 v[64:67], v[94:95], off offset:832
	s_waitcnt vmcnt(12)
	ds_bpermute_b32 v68, v134, v68
	ds_bpermute_b32 v69, v134, v69
	ds_bpermute_b32 v70, v134, v70
	ds_bpermute_b32 v71, v134, v71
	ds_bpermute_b32 v72, v134, v72
	ds_bpermute_b32 v73, v134, v73
	ds_bpermute_b32 v74, v134, v74
	ds_bpermute_b32 v75, v134, v75
	s_waitcnt lgkmcnt(0)
	v_mfma_f32_16x16x32_bf16 v[0:3], v[68:71], v[72:75], v[0:3]
	s_waitcnt vmcnt(10)
	ds_bpermute_b32 v20, v134, v20
	ds_bpermute_b32 v21, v134, v21
	ds_bpermute_b32 v22, v134, v22
	ds_bpermute_b32 v23, v134, v23
	ds_bpermute_b32 v32, v134, v32
	ds_bpermute_b32 v33, v134, v33
	ds_bpermute_b32 v34, v134, v34
	ds_bpermute_b32 v35, v134, v35
	s_waitcnt lgkmcnt(0)
	v_mfma_f32_16x16x32_bf16 v[0:3], v[20:23], v[32:35], v[0:3]
	global_load_dwordx4 v[20:23], v[92:93], off offset:896
	global_load_dwordx4 v[32:35], v[94:95], off offset:896
	s_waitcnt vmcnt(10)
	ds_bpermute_b32 v36, v134, v36
	ds_bpermute_b32 v37, v134, v37
	ds_bpermute_b32 v38, v134, v38
	ds_bpermute_b32 v39, v134, v39
	ds_bpermute_b32 v40, v134, v40
	ds_bpermute_b32 v41, v134, v41
	ds_bpermute_b32 v42, v134, v42
	ds_bpermute_b32 v43, v134, v43
	s_waitcnt lgkmcnt(0)
	v_mfma_f32_16x16x32_bf16 v[0:3], v[36:39], v[40:43], v[0:3]
	s_waitcnt vmcnt(7)
	ds_bpermute_b32 v24, v134, v24
	ds_bpermute_b32 v25, v134, v25
	ds_bpermute_b32 v26, v134, v26
	ds_bpermute_b32 v27, v134, v27
	ds_bpermute_b32 v48, v134, v48
	ds_bpermute_b32 v49, v134, v49
	ds_bpermute_b32 v50, v134, v50
	ds_bpermute_b32 v51, v134, v51
	s_waitcnt lgkmcnt(0)
	v_mfma_f32_16x16x32_bf16 v[0:3], v[24:27], v[48:51], v[0:3]
	global_load_dwordx4 v[24:27], v[92:93], off offset:960
	global_load_dwordx4 v[36:39], v[94:95], off offset:960
	s_waitcnt vmcnt(8)
	ds_bpermute_b32 v44, v134, v44
	ds_bpermute_b32 v45, v134, v45
	ds_bpermute_b32 v46, v134, v46
	ds_bpermute_b32 v47, v134, v47
	ds_bpermute_b32 v52, v134, v52
	ds_bpermute_b32 v53, v134, v53
	ds_bpermute_b32 v54, v134, v54
	ds_bpermute_b32 v55, v134, v55
	s_waitcnt lgkmcnt(0)
	v_mfma_f32_16x16x32_bf16 v[0:3], v[44:47], v[52:55], v[0:3]
	global_load_dwordx4 v[40:43], v[92:93], off offset:1024
	global_load_dwordx4 v[44:47], v[92:93], off offset:1088
	s_waitcnt vmcnt(7)
	ds_bpermute_b32 v28, v134, v28
	ds_bpermute_b32 v29, v134, v29
	ds_bpermute_b32 v30, v134, v30
	ds_bpermute_b32 v31, v134, v31
	ds_bpermute_b32 v60, v134, v60
	ds_bpermute_b32 v61, v134, v61
	ds_bpermute_b32 v62, v134, v62
	ds_bpermute_b32 v63, v134, v63
	s_waitcnt lgkmcnt(0)
	v_mfma_f32_16x16x32_bf16 v[0:3], v[28:31], v[60:63], v[0:3]
	global_load_dwordx4 v[28:31], v[94:95], off offset:1024
	global_load_dwordx4 v[48:51], v[94:95], off offset:1088
	global_load_dwordx4 v[52:55], v[92:93], off offset:1152
	s_waitcnt vmcnt(9)
; template <int MODE> ...
;     ...
;         if (MODE == 0) {
;             const int kb = kh * (K / 2);
;             const bf16_t* ap = A + (size_t)(rt * 16 + fr) * lda + kb + fq * 8;
;             const bf16_t* bp = Bt + (size_t)(ct * 16 + fr) * ldb + kb + fq * 8;
; #pragma unroll 16
;             for (int ks = 0; ks < K / 64; ++ks) {
;                 const bf16x8 af = *(const bf16x8*)(ap + ks * 32), bfv = *(const bf16x8*)(bp + ks * 32);
;                 tot = __builtin_amdgcn_mfma_f32_16x16x32_bf16(bfv, af, tot, 0, 0, 0);
;             }
;     ...
;         if (kh == 1) red[tw * 64 + lane] = tot;
	ds_bpermute_b32 v56, v134, v56
	ds_bpermute_b32 v57, v134, v57
	ds_bpermute_b32 v58, v134, v58
	ds_bpermute_b32 v59, v134, v59
	ds_bpermute_b32 v64, v134, v64
	ds_bpermute_b32 v65, v134, v65
	ds_bpermute_b32 v66, v134, v66
	ds_bpermute_b32 v67, v134, v67
	s_waitcnt lgkmcnt(0)
	v_mfma_f32_16x16x32_bf16 v[0:3], v[56:59], v[64:67], v[0:3]
	s_waitcnt vmcnt(7)
	ds_bpermute_b32 v20, v134, v20
	ds_bpermute_b32 v21, v134, v21
	ds_bpermute_b32 v22, v134, v22
	ds_bpermute_b32 v23, v134, v23
	ds_bpermute_b32 v32, v134, v32
	ds_bpermute_b32 v33, v134, v33
	ds_bpermute_b32 v34, v134, v34
	ds_bpermute_b32 v35, v134, v35
	s_waitcnt lgkmcnt(0)
	v_mfma_f32_16x16x32_bf16 v[0:3], v[20:23], v[32:35], v[0:3]
	global_load_dwordx4 v[20:23], v[94:95], off offset:1152
	s_waitcnt vmcnt(6)
	ds_bpermute_b32 v24, v134, v24
	ds_bpermute_b32 v25, v134, v25
	ds_bpermute_b32 v26, v134, v26
	ds_bpermute_b32 v27, v134, v27
	ds_bpermute_b32 v36, v134, v36
	ds_bpermute_b32 v37, v134, v37
	ds_bpermute_b32 v38, v134, v38
	ds_bpermute_b32 v39, v134, v39
	s_waitcnt lgkmcnt(0)
	v_mfma_f32_16x16x32_bf16 v[0:3], v[24:27], v[36:39], v[0:3]
	global_load_dwordx4 v[24:27], v[92:93], off offset:1216
	global_load_dwordx4 v[32:35], v[94:95], off offset:1216
	s_waitcnt vmcnt(5)
	ds_bpermute_b32 v40, v134, v40
	ds_bpermute_b32 v41, v134, v41
	ds_bpermute_b32 v42, v134, v42
	ds_bpermute_b32 v43, v134, v43
	ds_bpermute_b32 v28, v134, v28
	ds_bpermute_b32 v29, v134, v29
	ds_bpermute_b32 v30, v134, v30
	ds_bpermute_b32 v31, v134, v31
	s_waitcnt lgkmcnt(0)
	v_mfma_f32_16x16x32_bf16 v[0:3], v[40:43], v[28:31], v[0:3]
	global_load_dwordx4 v[28:31], v[92:93], off offset:1280
	global_load_dwordx4 v[36:39], v[94:95], off offset:1280
	global_load_dwordx4 v[40:43], v[92:93], off offset:1344
	s_waitcnt vmcnt(7)
	ds_bpermute_b32 v44, v134, v44
	ds_bpermute_b32 v45, v134, v45
	ds_bpermute_b32 v46, v134, v46
	ds_bpermute_b32 v47, v134, v47
	ds_bpermute_b32 v48, v134, v48
	ds_bpermute_b32 v49, v134, v49
	ds_bpermute_b32 v50, v134, v50
	ds_bpermute_b32 v51, v134, v51
	s_waitcnt lgkmcnt(0)
	v_mfma_f32_16x16x32_bf16 v[0:3], v[44:47], v[48:51], v[0:3]
	s_waitcnt vmcnt(5)
	ds_bpermute_b32 v52, v134, v52
	ds_bpermute_b32 v53, v134, v53
	ds_bpermute_b32 v54, v134, v54
	ds_bpermute_b32 v55, v134, v55
	ds_bpermute_b32 v20, v134, v20
	ds_bpermute_b32 v21, v134, v21
	ds_bpermute_b32 v22, v134, v22
	ds_bpermute_b32 v23, v134, v23
	s_waitcnt lgkmcnt(0)
	v_mfma_f32_16x16x32_bf16 v[0:3], v[52:55], v[20:23], v[0:3]
	global_load_dwordx4 v[20:23], v[94:95], off offset:1344
	s_waitcnt vmcnt(4)
	ds_bpermute_b32 v24, v134, v24
	ds_bpermute_b32 v25, v134, v25
	ds_bpermute_b32 v26, v134, v26
	ds_bpermute_b32 v27, v134, v27
	ds_bpermute_b32 v32, v134, v32
	ds_bpermute_b32 v33, v134, v33
	ds_bpermute_b32 v34, v134, v34
	ds_bpermute_b32 v35, v134, v35
	s_waitcnt lgkmcnt(0)
	v_mfma_f32_16x16x32_bf16 v[0:3], v[24:27], v[32:35], v[0:3]
	global_load_dwordx4 v[24:27], v[92:93], off offset:1408
	global_load_dwordx4 v[32:35], v[94:95], off offset:1408
	s_waitcnt vmcnt(4)
	ds_bpermute_b32 v28, v134, v28
	ds_bpermute_b32 v29, v134, v29
	ds_bpermute_b32 v30, v134, v30
	ds_bpermute_b32 v31, v134, v31
	ds_bpermute_b32 v36, v134, v36
	ds_bpermute_b32 v37, v134, v37
	ds_bpermute_b32 v38, v134, v38
	ds_bpermute_b32 v39, v134, v39
	s_waitcnt lgkmcnt(0)
	v_mfma_f32_16x16x32_bf16 v[0:3], v[28:31], v[36:39], v[0:3]
	global_load_dwordx4 v[28:31], v[92:93], off offset:1472
	s_waitcnt vmcnt(3)
	ds_bpermute_b32 v40, v134, v40
	ds_bpermute_b32 v41, v134, v41
	ds_bpermute_b32 v42, v134, v42
	ds_bpermute_b32 v43, v134, v43
	ds_bpermute_b32 v20, v134, v20
	ds_bpermute_b32 v21, v134, v21
	ds_bpermute_b32 v22, v134, v22
	ds_bpermute_b32 v23, v134, v23
	s_waitcnt lgkmcnt(0)
	v_mfma_f32_16x16x32_bf16 v[0:3], v[40:43], v[20:23], v[0:3]
	global_load_dwordx4 v[20:23], v[94:95], off offset:1472
	s_waitcnt vmcnt(2)
	ds_bpermute_b32 v24, v134, v24
	ds_bpermute_b32 v25, v134, v25
	ds_bpermute_b32 v26, v134, v26
	ds_bpermute_b32 v27, v134, v27
	ds_bpermute_b32 v32, v134, v32
	ds_bpermute_b32 v33, v134, v33
	ds_bpermute_b32 v34, v134, v34
	ds_bpermute_b32 v35, v134, v35
	s_waitcnt lgkmcnt(0)
	v_mfma_f32_16x16x32_bf16 v[0:3], v[24:27], v[32:35], v[0:3]
	s_waitcnt vmcnt(0)
	ds_bpermute_b32 v28, v134, v28
	ds_bpermute_b32 v29, v134, v29
	ds_bpermute_b32 v30, v134, v30
	ds_bpermute_b32 v31, v134, v31
	ds_bpermute_b32 v20, v134, v20
	ds_bpermute_b32 v21, v134, v21
	ds_bpermute_b32 v22, v134, v22
	ds_bpermute_b32 v23, v134, v23
	s_waitcnt lgkmcnt(0)
	v_mfma_f32_16x16x32_bf16 v[0:3], v[28:31], v[20:23], v[0:3]
	s_cbranch_vccnz .LBB0_220
	s_nop 6
	ds_write_b128 v11, v[0:3]

; template <int MODE> ...
;     ...
;         if (MODE == 0) {
;             const int kb = kh * (K / 2);
;             const bf16_t* ap = A + (size_t)(rt * 16 + fr) * lda + kb + fq * 8;
;             const bf16_t* bp = Bt + (size_t)(ct * 16 + fr) * ldb + kb + fq * 8;
; #pragma unroll 16
;             for (int ks = 0; ks < K / 64; ++ks) {
;                 const bf16x8 af = *(const bf16x8*)(ap + ks * 32), bfv = *(const bf16x8*)(bp + ks * 32);
;                 tot = __builtin_amdgcn_mfma_f32_16x16x32_bf16(bfv, af, tot, 0, 0, 0);
;             }
.LBB0_918:
	v_mbcnt_lo_u32_b32 v128, -1, 0
	v_mbcnt_hi_u32_b32 v128, -1, v128
	v_lshrrev_b32_e32 v129, 2, v128
	v_and_b32_e32 v132, 15, v128
	v_sub_u32_e32 v129, v129, v132
	v_mul_i32_i24_e32 v130, 0x1000, v129
	v_and_b32_e32 v133, 3, v128
	v_lshrrev_b32_e32 v135, 4, v128
	v_sub_u32_e32 v133, v133, v135
	v_lshlrev_b32_e32 v133, 4, v133
	v_add_u32_e32 v130, v130, v133
	v_ashrrev_i32_e32 v131, 31, v130
	v_lshl_or_b32 v134, v132, 2, v135
	v_lshlrev_b32_e32 v134, 2, v134
	s_lshl_b32 s0, s2, 16
	s_and_b32 s0, s0, 0x7c0000
	v_lshl_or_b32 v152, v177, 12, s0
	s_ashr_i32 s0, s2, 3
	v_and_or_b32 v12, s0, -16, v234
	v_ashrrev_i32_e32 v13, 31, v12
	v_lshlrev_b64 v[0:1], 12, v[12:13]
	v_lshl_add_u64 v[10:11], v[6:7], 0, v[152:153]
	v_lshl_add_u64 v[10:11], v[10:11], 0, v[130:131]
	v_lshl_add_u64 v[14:15], v[8:9], 0, v[0:1]
	v_lshl_add_u64 v[14:15], v[14:15], 0, v[130:131]
	s_mov_b64 s[0:1], 0
	v_mov_b32_e32 v0, 0
	v_mov_b32_e32 v1, v153
	v_mov_b32_e32 v2, v153
	v_mov_b32_e32 v3, v153
.LBB0_919:
	v_lshl_add_u64 v[72:73], v[10:11], 0, s[0:1]
	v_lshl_add_u64 v[70:71], v[14:15], 0, s[0:1]
	global_load_dwordx4 v[22:25], v[72:73], off offset:-512
	global_load_dwordx4 v[26:29], v[72:73], off offset:-448
	global_load_dwordx4 v[30:33], v[70:71], off offset:-512
	global_load_dwordx4 v[34:37], v[70:71], off offset:-448
	global_load_dwordx4 v[38:41], v[72:73], off offset:-384
	global_load_dwordx4 v[42:45], v[72:73], off offset:-320
	global_load_dwordx4 v[46:49], v[70:71], off offset:-384
	global_load_dwordx4 v[50:53], v[70:71], off offset:-320
	global_load_dwordx4 v[54:57], v[72:73], off offset:-256
	global_load_dwordx4 v[58:61], v[72:73], off offset:-192
	global_load_dwordx4 v[62:65], v[70:71], off offset:-256
	global_load_dwordx4 v[66:69], v[70:71], off offset:-192
	s_add_u32 s0, s0, 0x400
	s_addc_u32 s1, s1, 0
	s_cmpk_eq_i32 s0, 0x800
	s_waitcnt vmcnt(9)
	ds_bpermute_b32 v22, v134, v22
	ds_bpermute_b32 v23, v134, v23
	ds_bpermute_b32 v24, v134, v24
	ds_bpermute_b32 v25, v134, v25
	ds_bpermute_b32 v30, v134, v30
	ds_bpermute_b32 v31, v134, v31
	ds_bpermute_b32 v32, v134, v32
	ds_bpermute_b32 v33, v134, v33
	s_waitcnt lgkmcnt(0)
	v_mfma_f32_16x16x32_bf16 v[0:3], v[22:25], v[30:33], v[0:3]
	global_load_dwordx4 v[22:25], v[72:73], off offset:-128
	s_waitcnt vmcnt(9)
	ds_bpermute_b32 v26, v134, v26
	ds_bpermute_b32 v27, v134, v27
	ds_bpermute_b32 v28, v134, v28
	ds_bpermute_b32 v29, v134, v29
	ds_bpermute_b32 v34, v134, v34
	ds_bpermute_b32 v35, v134, v35
	ds_bpermute_b32 v36, v134, v36
	ds_bpermute_b32 v37, v134, v37
	s_waitcnt lgkmcnt(0)
	v_mfma_f32_16x16x32_bf16 v[0:3], v[26:29], v[34:37], v[0:3]
	global_load_dwordx4 v[26:29], v[70:71], off offset:-128
	global_load_dwordx4 v[30:33], v[72:73], off offset:-64
	global_load_dwordx4 v[34:37], v[70:71], off offset:-64
	s_waitcnt vmcnt(9)
	ds_bpermute_b32 v38, v134, v38
	ds_bpermute_b32 v39, v134, v39
	ds_bpermute_b32 v40, v134, v40
	ds_bpermute_b32 v41, v134, v41
	ds_bpermute_b32 v46, v134, v46
	ds_bpermute_b32 v47, v134, v47
	ds_bpermute_b32 v48, v134, v48
	ds_bpermute_b32 v49, v134, v49
	s_waitcnt lgkmcnt(0)
	v_mfma_f32_16x16x32_bf16 v[0:3], v[38:41], v[46:49], v[0:3]
	s_waitcnt vmcnt(8)
	ds_bpermute_b32 v42, v134, v42
	ds_bpermute_b32 v43, v134, v43
	ds_bpermute_b32 v44, v134, v44
	ds_bpermute_b32 v45, v134, v45
	ds_bpermute_b32 v50, v134, v50
	ds_bpermute_b32 v51, v134, v51
	ds_bpermute_b32 v52, v134, v52
	ds_bpermute_b32 v53, v134, v53
	s_waitcnt lgkmcnt(0)
	v_mfma_f32_16x16x32_bf16 v[0:3], v[42:45], v[50:53], v[0:3]
	global_load_dwordx4 v[38:41], v[72:73], off
	global_load_dwordx4 v[42:45], v[72:73], off offset:64
	global_load_dwordx4 v[46:49], v[70:71], off
	global_load_dwordx4 v[50:53], v[70:71], off offset:64
	s_waitcnt vmcnt(9)
	ds_bpermute_b32 v54, v134, v54
	ds_bpermute_b32 v55, v134, v55
	ds_bpermute_b32 v56, v134, v56
	ds_bpermute_b32 v57, v134, v57
	ds_bpermute_b32 v62, v134, v62
	ds_bpermute_b32 v63, v134, v63
	ds_bpermute_b32 v64, v134, v64
	ds_bpermute_b32 v65, v134, v65
	s_waitcnt lgkmcnt(0)
	v_mfma_f32_16x16x32_bf16 v[0:3], v[54:57], v[62:65], v[0:3]
	global_load_dwordx4 v[54:57], v[72:73], off offset:128
	s_waitcnt vmcnt(9)
	ds_bpermute_b32 v58, v134, v58
	ds_bpermute_b32 v59, v134, v59
	ds_bpermute_b32 v60, v134, v60
	ds_bpermute_b32 v61, v134, v61
	ds_bpermute_b32 v66, v134, v66
	ds_bpermute_b32 v67, v134, v67
	ds_bpermute_b32 v68, v134, v68
	ds_bpermute_b32 v69, v134, v69
	s_waitcnt lgkmcnt(0)
; template <int MODE> ...
;     ...
;         if (MODE == 0) {
;             const int kb = kh * (K / 2);
;             const bf16_t* ap = A + (size_t)(rt * 16 + fr) * lda + kb + fq * 8;
;             const bf16_t* bp = Bt + (size_t)(ct * 16 + fr) * ldb + kb + fq * 8;
; #pragma unroll 16
;             for (int ks = 0; ks < K / 64; ++ks) {
;                 const bf16x8 af = *(const bf16x8*)(ap + ks * 32), bfv = *(const bf16x8*)(bp + ks * 32);
;                 tot = __builtin_amdgcn_mfma_f32_16x16x32_bf16(bfv, af, tot, 0, 0, 0);
;             }
;     ...
;         if (kh == 1) red[tw * 64 + lane] = tot;
	v_mfma_f32_16x16x32_bf16 v[0:3], v[58:61], v[66:69], v[0:3]
	s_waitcnt vmcnt(7)
	ds_bpermute_b32 v22, v134, v22
	ds_bpermute_b32 v23, v134, v23
	ds_bpermute_b32 v24, v134, v24
	ds_bpermute_b32 v25, v134, v25
	ds_bpermute_b32 v26, v134, v26
	ds_bpermute_b32 v27, v134, v27
	ds_bpermute_b32 v28, v134, v28
	ds_bpermute_b32 v29, v134, v29
	s_waitcnt lgkmcnt(0)
	v_mfma_f32_16x16x32_bf16 v[0:3], v[22:25], v[26:29], v[0:3]
	global_load_dwordx4 v[22:25], v[70:71], off offset:128
	s_waitcnt vmcnt(6)
	ds_bpermute_b32 v30, v134, v30
	ds_bpermute_b32 v31, v134, v31
	ds_bpermute_b32 v32, v134, v32
	ds_bpermute_b32 v33, v134, v33
	ds_bpermute_b32 v34, v134, v34
	ds_bpermute_b32 v35, v134, v35
	ds_bpermute_b32 v36, v134, v36
	ds_bpermute_b32 v37, v134, v37
	s_waitcnt lgkmcnt(0)
	v_mfma_f32_16x16x32_bf16 v[0:3], v[30:33], v[34:37], v[0:3]
	global_load_dwordx4 v[26:29], v[72:73], off offset:192
	global_load_dwordx4 v[30:33], v[70:71], off offset:192
	s_waitcnt vmcnt(5)
	ds_bpermute_b32 v38, v134, v38
	ds_bpermute_b32 v39, v134, v39
	ds_bpermute_b32 v40, v134, v40
	ds_bpermute_b32 v41, v134, v41
	ds_bpermute_b32 v46, v134, v46
	ds_bpermute_b32 v47, v134, v47
	ds_bpermute_b32 v48, v134, v48
	ds_bpermute_b32 v49, v134, v49
	s_waitcnt lgkmcnt(0)
	v_mfma_f32_16x16x32_bf16 v[0:3], v[38:41], v[46:49], v[0:3]
	global_load_dwordx4 v[34:37], v[72:73], off offset:256
	global_load_dwordx4 v[38:41], v[70:71], off offset:256
	s_waitcnt vmcnt(6)
	ds_bpermute_b32 v42, v134, v42
	ds_bpermute_b32 v43, v134, v43
	ds_bpermute_b32 v44, v134, v44
	ds_bpermute_b32 v45, v134, v45
	ds_bpermute_b32 v50, v134, v50
	ds_bpermute_b32 v51, v134, v51
	ds_bpermute_b32 v52, v134, v52
	ds_bpermute_b32 v53, v134, v53
	s_waitcnt lgkmcnt(0)
	v_mfma_f32_16x16x32_bf16 v[0:3], v[42:45], v[50:53], v[0:3]
	global_load_dwordx4 v[42:45], v[72:73], off offset:320
	s_waitcnt vmcnt(5)
	ds_bpermute_b32 v54, v134, v54
	ds_bpermute_b32 v55, v134, v55
	ds_bpermute_b32 v56, v134, v56
	ds_bpermute_b32 v57, v134, v57
	ds_bpermute_b32 v22, v134, v22
	ds_bpermute_b32 v23, v134, v23
	ds_bpermute_b32 v24, v134, v24
	ds_bpermute_b32 v25, v134, v25
	s_waitcnt lgkmcnt(0)
	v_mfma_f32_16x16x32_bf16 v[0:3], v[54:57], v[22:25], v[0:3]
	global_load_dwordx4 v[22:25], v[70:71], off offset:320
	s_waitcnt vmcnt(4)
	ds_bpermute_b32 v26, v134, v26
	ds_bpermute_b32 v27, v134, v27
	ds_bpermute_b32 v28, v134, v28
	ds_bpermute_b32 v29, v134, v29
	ds_bpermute_b32 v30, v134, v30
	ds_bpermute_b32 v31, v134, v31
	ds_bpermute_b32 v32, v134, v32
	ds_bpermute_b32 v33, v134, v33
	s_waitcnt lgkmcnt(0)
	v_mfma_f32_16x16x32_bf16 v[0:3], v[26:29], v[30:33], v[0:3]
	global_load_dwordx4 v[26:29], v[72:73], off offset:384
	global_load_dwordx4 v[30:33], v[70:71], off offset:384
	s_waitcnt vmcnt(4)
	ds_bpermute_b32 v34, v134, v34
	ds_bpermute_b32 v35, v134, v35
	ds_bpermute_b32 v36, v134, v36
	ds_bpermute_b32 v37, v134, v37
	ds_bpermute_b32 v38, v134, v38
	ds_bpermute_b32 v39, v134, v39
	ds_bpermute_b32 v40, v134, v40
	ds_bpermute_b32 v41, v134, v41
	s_waitcnt lgkmcnt(0)
	v_mfma_f32_16x16x32_bf16 v[0:3], v[34:37], v[38:41], v[0:3]
	global_load_dwordx4 v[34:37], v[72:73], off offset:448
	s_waitcnt vmcnt(3)
	ds_bpermute_b32 v42, v134, v42
	ds_bpermute_b32 v43, v134, v43
	ds_bpermute_b32 v44, v134, v44
	ds_bpermute_b32 v45, v134, v45
	ds_bpermute_b32 v22, v134, v22
	ds_bpermute_b32 v23, v134, v23
	ds_bpermute_b32 v24, v134, v24
	ds_bpermute_b32 v25, v134, v25
	s_waitcnt lgkmcnt(0)
	v_mfma_f32_16x16x32_bf16 v[0:3], v[42:45], v[22:25], v[0:3]
	global_load_dwordx4 v[22:25], v[70:71], off offset:448
	s_waitcnt vmcnt(2)
	ds_bpermute_b32 v26, v134, v26
	ds_bpermute_b32 v27, v134, v27
	ds_bpermute_b32 v28, v134, v28
	ds_bpermute_b32 v29, v134, v29
	ds_bpermute_b32 v30, v134, v30
	ds_bpermute_b32 v31, v134, v31
	ds_bpermute_b32 v32, v134, v32
	ds_bpermute_b32 v33, v134, v33
	s_waitcnt lgkmcnt(0)
	v_mfma_f32_16x16x32_bf16 v[0:3], v[26:29], v[30:33], v[0:3]
	s_waitcnt vmcnt(0)
	ds_bpermute_b32 v34, v134, v34
	ds_bpermute_b32 v35, v134, v35
	ds_bpermute_b32 v36, v134, v36
	ds_bpermute_b32 v37, v134, v37
	ds_bpermute_b32 v22, v134, v22
	ds_bpermute_b32 v23, v134, v23
	ds_bpermute_b32 v24, v134, v24
	ds_bpermute_b32 v25, v134, v25
	s_waitcnt lgkmcnt(0)
	v_mfma_f32_16x16x32_bf16 v[0:3], v[34:37], v[22:25], v[0:3]
	s_cbranch_scc0 .LBB0_919
	s_and_b64 vcc, exec, s[12:13]
	s_cbranch_vccz .LBB0_922
	s_nop 4
	ds_write_b128 v5, v[0:3]

; template <int MODE> ...
;     ...
;         if (MODE == 0) {
;             const int kb = kh * (K / 2);
;             const bf16_t* ap = A + (size_t)(rt * 16 + fr) * lda + kb + fq * 8;
;             const bf16_t* bp = Bt + (size_t)(ct * 16 + fr) * ldb + kb + fq * 8;
; #pragma unroll 16
;             for (int ks = 0; ks < K / 64; ++ks) {
;                 const bf16x8 af = *(const bf16x8*)(ap + ks * 32), bfv = *(const bf16x8*)(bp + ks * 32);
;                 tot = __builtin_amdgcn_mfma_f32_16x16x32_bf16(bfv, af, tot, 0, 0, 0);
;             }
.LBB0_1099:
	v_mbcnt_lo_u32_b32 v128, -1, 0
	v_mbcnt_hi_u32_b32 v128, -1, v128
	v_lshrrev_b32_e32 v129, 2, v128
	v_and_b32_e32 v132, 15, v128
	v_sub_u32_e32 v129, v129, v132
	v_mul_i32_i24_e32 v130, 0x2c00, v129
	v_and_b32_e32 v133, 3, v128
	v_lshrrev_b32_e32 v135, 4, v128
	v_sub_u32_e32 v133, v133, v135
	v_lshlrev_b32_e32 v133, 4, v133
	v_add_u32_e32 v130, v130, v133
	v_ashrrev_i32_e32 v131, 31, v130
	v_lshl_or_b32 v134, v132, 2, v135
	v_lshlrev_b32_e32 v134, 2, v134
	s_and_b32 s0, s15, 0x7c
	s_or_b32 s0, s0, s56
	s_lshl_b32 s0, s0, 4
	v_or_b32_e32 v0, s0, v234
	v_mul_u32_u24_e32 v0, 0x1600, v0
	v_lshlrev_b32_e32 v180, 1, v0
	v_lshl_add_u64 v[2:3], v[6:7], 0, v[180:181]
	v_lshl_add_u64 v[2:3], v[2:3], 0, v[130:131]
	global_load_dwordx4 v[16:19], v[2:3], off
	s_ashr_i32 s1, s15, 3
	v_and_or_b32 v12, s1, -16, v234
	v_mad_i64_i32 v[0:1], s[22:23], v12, s18, v[4:5]
	v_lshl_add_u64 v[0:1], v[0:1], 0, v[130:131]
	global_load_dwordx4 v[20:23], v[0:1], off
	global_load_dwordx4 v[24:27], v[2:3], off offset:64
	global_load_dwordx4 v[28:31], v[0:1], off offset:64
	global_load_dwordx4 v[32:35], v[2:3], off offset:128
	global_load_dwordx4 v[36:39], v[2:3], off offset:192
	global_load_dwordx4 v[40:43], v[0:1], off offset:128
	global_load_dwordx4 v[44:47], v[0:1], off offset:192
	global_load_dwordx4 v[48:51], v[2:3], off offset:256
	global_load_dwordx4 v[52:55], v[2:3], off offset:320
	global_load_dwordx4 v[56:59], v[0:1], off offset:256
	global_load_dwordx4 v[60:63], v[0:1], off offset:320
	global_load_dwordx4 v[64:67], v[2:3], off offset:384
	global_load_dwordx4 v[68:71], v[2:3], off offset:448
	global_load_dwordx4 v[72:75], v[0:1], off offset:384
	global_load_dwordx4 v[76:79], v[0:1], off offset:448
	global_load_dwordx4 v[80:83], v[2:3], off offset:512
	global_load_dwordx4 v[84:87], v[2:3], off offset:576
	global_load_dwordx4 v[88:91], v[0:1], off offset:512
	global_load_dwordx4 v[92:95], v[0:1], off offset:576
	global_load_dwordx4 v[96:99], v[2:3], off offset:640
	global_load_dwordx4 v[100:103], v[0:1], off offset:640
	global_load_dwordx4 v[104:107], v[2:3], off offset:704
	global_load_dwordx4 v[108:111], v[0:1], off offset:704
	global_load_dwordx4 v[112:115], v[2:3], off offset:768
	global_load_dwordx4 v[116:119], v[2:3], off offset:832
	s_waitcnt vmcnt(24)
	ds_bpermute_b32 v16, v134, v16
	ds_bpermute_b32 v17, v134, v17
	ds_bpermute_b32 v18, v134, v18
	ds_bpermute_b32 v19, v134, v19
	ds_bpermute_b32 v20, v134, v20
	ds_bpermute_b32 v21, v134, v21
	ds_bpermute_b32 v22, v134, v22
	ds_bpermute_b32 v23, v134, v23
	s_waitcnt lgkmcnt(0)
	v_mfma_f32_16x16x32_bf16 v[16:19], v[16:19], v[20:23], 0
	global_load_dwordx4 v[20:23], v[0:1], off offset:768
	global_load_dwordx4 v[120:123], v[0:1], off offset:832
	s_waitcnt vmcnt(24)
	ds_bpermute_b32 v24, v134, v24
	ds_bpermute_b32 v25, v134, v25
	ds_bpermute_b32 v26, v134, v26
	ds_bpermute_b32 v27, v134, v27
	ds_bpermute_b32 v28, v134, v28
	ds_bpermute_b32 v29, v134, v29
	ds_bpermute_b32 v30, v134, v30
	ds_bpermute_b32 v31, v134, v31
	s_waitcnt lgkmcnt(0)
	v_mfma_f32_16x16x32_bf16 v[16:19], v[24:27], v[28:31], v[16:19]
	global_load_dwordx4 v[24:27], v[2:3], off offset:896
	global_load_dwordx4 v[28:31], v[0:1], off offset:896
	s_waitcnt vmcnt(23)
	ds_bpermute_b32 v32, v134, v32
	ds_bpermute_b32 v33, v134, v33
	ds_bpermute_b32 v34, v134, v34
	ds_bpermute_b32 v35, v134, v35
	ds_bpermute_b32 v40, v134, v40
	ds_bpermute_b32 v41, v134, v41
	ds_bpermute_b32 v42, v134, v42
	ds_bpermute_b32 v43, v134, v43
	s_waitcnt lgkmcnt(0)
	v_mfma_f32_16x16x32_bf16 v[16:19], v[32:35], v[40:43], v[16:19]
	global_load_dwordx4 v[32:35], v[2:3], off offset:960
	global_load_dwordx4 v[40:43], v[0:1], off offset:960
	s_waitcnt vmcnt(24)
	ds_bpermute_b32 v36, v134, v36
	ds_bpermute_b32 v37, v134, v37
	ds_bpermute_b32 v38, v134, v38
	ds_bpermute_b32 v39, v134, v39
	ds_bpermute_b32 v44, v134, v44
	ds_bpermute_b32 v45, v134, v45
	ds_bpermute_b32 v46, v134, v46
	ds_bpermute_b32 v47, v134, v47
	s_waitcnt lgkmcnt(0)
	v_mfma_f32_16x16x32_bf16 v[16:19], v[36:39], v[44:47], v[16:19]
	global_load_dwordx4 v[36:39], v[2:3], off offset:1024
	global_load_dwordx4 v[44:47], v[2:3], off offset:1088
	s_waitcnt vmcnt(23)
	ds_bpermute_b32 v48, v134, v48
	ds_bpermute_b32 v49, v134, v49
	ds_bpermute_b32 v50, v134, v50
	ds_bpermute_b32 v51, v134, v51
	ds_bpermute_b32 v56, v134, v56
	ds_bpermute_b32 v57, v134, v57
	ds_bpermute_b32 v58, v134, v58
	ds_bpermute_b32 v59, v134, v59
	s_waitcnt lgkmcnt(0)
	v_mfma_f32_16x16x32_bf16 v[16:19], v[48:51], v[56:59], v[16:19]
	global_load_dwordx4 v[48:51], v[0:1], off offset:1024
	global_load_dwordx4 v[56:59], v[0:1], off offset:1088
	s_waitcnt vmcnt(24)
	ds_bpermute_b32 v52, v134, v52
	ds_bpermute_b32 v53, v134, v53
	ds_bpermute_b32 v54, v134, v54
	ds_bpermute_b32 v55, v134, v55
	ds_bpermute_b32 v60, v134, v60
	ds_bpermute_b32 v61, v134, v61
	ds_bpermute_b32 v62, v134, v62
	ds_bpermute_b32 v63, v134, v63
	s_waitcnt lgkmcnt(0)
	v_mfma_f32_16x16x32_bf16 v[16:19], v[52:55], v[60:63], v[16:19]
	global_load_dwordx4 v[52:55], v[2:3], off offset:1152
	global_load_dwordx4 v[60:63], v[2:3], off offset:1216
	s_waitcnt vmcnt(23)
	ds_bpermute_b32 v64, v134, v64
	ds_bpermute_b32 v65, v134, v65
	ds_bpermute_b32 v66, v134, v66
	ds_bpermute_b32 v67, v134, v67
	ds_bpermute_b32 v72, v134, v72
	ds_bpermute_b32 v73, v134, v73
	ds_bpermute_b32 v74, v134, v74
	ds_bpermute_b32 v75, v134, v75
	s_waitcnt lgkmcnt(0)
	v_mfma_f32_16x16x32_bf16 v[16:19], v[64:67], v[72:75], v[16:19]
	global_load_dwordx4 v[64:67], v[0:1], off offset:1152
	global_load_dwordx4 v[72:75], v[0:1], off offset:1216
	s_waitcnt vmcnt(24)
; template <int MODE> ...
;     ...
;         if (MODE == 0) {
;             const int kb = kh * (K / 2);
;             const bf16_t* ap = A + (size_t)(rt * 16 + fr) * lda + kb + fq * 8;
;             const bf16_t* bp = Bt + (size_t)(ct * 16 + fr) * ldb + kb + fq * 8;
; #pragma unroll 16
;             for (int ks = 0; ks < K / 64; ++ks) {
;                 const bf16x8 af = *(const bf16x8*)(ap + ks * 32), bfv = *(const bf16x8*)(bp + ks * 32);
;                 tot = __builtin_amdgcn_mfma_f32_16x16x32_bf16(bfv, af, tot, 0, 0, 0);
;             }
	ds_bpermute_b32 v68, v134, v68
	ds_bpermute_b32 v69, v134, v69
	ds_bpermute_b32 v70, v134, v70
	ds_bpermute_b32 v71, v134, v71
	ds_bpermute_b32 v76, v134, v76
	ds_bpermute_b32 v77, v134, v77
	ds_bpermute_b32 v78, v134, v78
	ds_bpermute_b32 v79, v134, v79
	s_waitcnt lgkmcnt(0)
	v_mfma_f32_16x16x32_bf16 v[16:19], v[68:71], v[76:79], v[16:19]
	global_load_dwordx4 v[68:71], v[2:3], off offset:1280
	global_load_dwordx4 v[76:79], v[2:3], off offset:1344
	s_waitcnt vmcnt(23)
	ds_bpermute_b32 v80, v134, v80
	ds_bpermute_b32 v81, v134, v81
	ds_bpermute_b32 v82, v134, v82
	ds_bpermute_b32 v83, v134, v83
	ds_bpermute_b32 v88, v134, v88
	ds_bpermute_b32 v89, v134, v89
	ds_bpermute_b32 v90, v134, v90
	ds_bpermute_b32 v91, v134, v91
	s_waitcnt lgkmcnt(0)
	v_mfma_f32_16x16x32_bf16 v[16:19], v[80:83], v[88:91], v[16:19]
	global_load_dwordx4 v[80:83], v[0:1], off offset:1280
	global_load_dwordx4 v[88:91], v[0:1], off offset:1344
	s_waitcnt vmcnt(24)
	ds_bpermute_b32 v84, v134, v84
	ds_bpermute_b32 v85, v134, v85
	ds_bpermute_b32 v86, v134, v86
	ds_bpermute_b32 v87, v134, v87
	ds_bpermute_b32 v92, v134, v92
	ds_bpermute_b32 v93, v134, v93
	ds_bpermute_b32 v94, v134, v94
	ds_bpermute_b32 v95, v134, v95
	s_waitcnt lgkmcnt(0)
	v_mfma_f32_16x16x32_bf16 v[16:19], v[84:87], v[92:95], v[16:19]
	global_load_dwordx4 v[84:87], v[2:3], off offset:1408
	global_load_dwordx4 v[92:95], v[0:1], off offset:1408
	s_waitcnt vmcnt(24)
	ds_bpermute_b32 v96, v134, v96
	ds_bpermute_b32 v97, v134, v97
	ds_bpermute_b32 v98, v134, v98
	ds_bpermute_b32 v99, v134, v99
	ds_bpermute_b32 v100, v134, v100
	ds_bpermute_b32 v101, v134, v101
	ds_bpermute_b32 v102, v134, v102
	ds_bpermute_b32 v103, v134, v103
	s_waitcnt lgkmcnt(0)
	v_mfma_f32_16x16x32_bf16 v[16:19], v[96:99], v[100:103], v[16:19]
	global_load_dwordx4 v[96:99], v[2:3], off offset:1472
	global_load_dwordx4 v[100:103], v[0:1], off offset:1472
	s_waitcnt vmcnt(24)
	ds_bpermute_b32 v104, v134, v104
	ds_bpermute_b32 v105, v134, v105
	ds_bpermute_b32 v106, v134, v106
	ds_bpermute_b32 v107, v134, v107
	ds_bpermute_b32 v108, v134, v108
	ds_bpermute_b32 v109, v134, v109
	ds_bpermute_b32 v110, v134, v110
	ds_bpermute_b32 v111, v134, v111
	s_waitcnt lgkmcnt(0)
	v_mfma_f32_16x16x32_bf16 v[16:19], v[104:107], v[108:111], v[16:19]
	s_waitcnt vmcnt(21)
	ds_bpermute_b32 v112, v134, v112
	ds_bpermute_b32 v113, v134, v113
	ds_bpermute_b32 v114, v134, v114
	ds_bpermute_b32 v115, v134, v115
	ds_bpermute_b32 v20, v134, v20
	ds_bpermute_b32 v21, v134, v21
	ds_bpermute_b32 v22, v134, v22
	ds_bpermute_b32 v23, v134, v23
	s_waitcnt lgkmcnt(0)
	v_mfma_f32_16x16x32_bf16 v[16:19], v[112:115], v[20:23], v[16:19]
	global_load_dwordx4 v[20:23], v[2:3], off offset:1536
	global_load_dwordx4 v[104:107], v[2:3], off offset:1600
	global_load_dwordx4 v[108:111], v[0:1], off offset:1536
	global_load_dwordx4 v[112:115], v[0:1], off offset:1600
	s_waitcnt vmcnt(24)
	ds_bpermute_b32 v116, v134, v116
	ds_bpermute_b32 v117, v134, v117
	ds_bpermute_b32 v118, v134, v118
	ds_bpermute_b32 v119, v134, v119
	ds_bpermute_b32 v120, v134, v120
	ds_bpermute_b32 v121, v134, v121
	ds_bpermute_b32 v122, v134, v122
	ds_bpermute_b32 v123, v134, v123
	s_waitcnt lgkmcnt(0)
	v_mfma_f32_16x16x32_bf16 v[16:19], v[116:119], v[120:123], v[16:19]
	s_waitcnt vmcnt(22)
	ds_bpermute_b32 v24, v134, v24
	ds_bpermute_b32 v25, v134, v25
	ds_bpermute_b32 v26, v134, v26
	ds_bpermute_b32 v27, v134, v27
	ds_bpermute_b32 v28, v134, v28
	ds_bpermute_b32 v29, v134, v29
	ds_bpermute_b32 v30, v134, v30
	ds_bpermute_b32 v31, v134, v31
	s_waitcnt lgkmcnt(0)
	v_mfma_f32_16x16x32_bf16 v[16:19], v[24:27], v[28:31], v[16:19]
	global_load_dwordx4 v[24:27], v[2:3], off offset:1664
	global_load_dwordx4 v[28:31], v[0:1], off offset:1664
	s_waitcnt vmcnt(22)
	ds_bpermute_b32 v32, v134, v32
	ds_bpermute_b32 v33, v134, v33
	ds_bpermute_b32 v34, v134, v34
	ds_bpermute_b32 v35, v134, v35
	ds_bpermute_b32 v40, v134, v40
	ds_bpermute_b32 v41, v134, v41
	ds_bpermute_b32 v42, v134, v42
	ds_bpermute_b32 v43, v134, v43
	s_waitcnt lgkmcnt(0)
	v_mfma_f32_16x16x32_bf16 v[16:19], v[32:35], v[40:43], v[16:19]
	global_load_dwordx4 v[32:35], v[2:3], off offset:1728
	global_load_dwordx4 v[40:43], v[0:1], off offset:1728
	s_waitcnt vmcnt(21)
	ds_bpermute_b32 v36, v134, v36
	ds_bpermute_b32 v37, v134, v37
	ds_bpermute_b32 v38, v134, v38
	ds_bpermute_b32 v39, v134, v39
	ds_bpermute_b32 v48, v134, v48
	ds_bpermute_b32 v49, v134, v49
	ds_bpermute_b32 v50, v134, v50
	ds_bpermute_b32 v51, v134, v51
	s_waitcnt lgkmcnt(0)
	v_mfma_f32_16x16x32_bf16 v[16:19], v[36:39], v[48:51], v[16:19]
	global_load_dwordx4 v[36:39], v[2:3], off offset:1792
	global_load_dwordx4 v[48:51], v[2:3], off offset:1856
	s_waitcnt vmcnt(22)
	ds_bpermute_b32 v44, v134, v44
	ds_bpermute_b32 v45, v134, v45
	ds_bpermute_b32 v46, v134, v46
	ds_bpermute_b32 v47, v134, v47
	ds_bpermute_b32 v56, v134, v56
	ds_bpermute_b32 v57, v134, v57
	ds_bpermute_b32 v58, v134, v58
	ds_bpermute_b32 v59, v134, v59
	s_waitcnt lgkmcnt(0)
	v_mfma_f32_16x16x32_bf16 v[16:19], v[44:47], v[56:59], v[16:19]
	global_load_dwordx4 v[44:47], v[0:1], off offset:1792
	global_load_dwordx4 v[56:59], v[0:1], off offset:1856
	s_waitcnt vmcnt(21)
	ds_bpermute_b32 v52, v134, v52
	ds_bpermute_b32 v53, v134, v53
	ds_bpermute_b32 v54, v134, v54
	ds_bpermute_b32 v55, v134, v55
	ds_bpermute_b32 v64, v134, v64
	ds_bpermute_b32 v65, v134, v65
	ds_bpermute_b32 v66, v134, v66
	ds_bpermute_b32 v67, v134, v67
	s_waitcnt lgkmcnt(0)
	v_mfma_f32_16x16x32_bf16 v[16:19], v[52:55], v[64:67], v[16:19]
	global_load_dwordx4 v[52:55], v[2:3], off offset:1920
	global_load_dwordx4 v[64:67], v[2:3], off offset:1984
	s_waitcnt vmcnt(22)
; template <int MODE> ...
;     ...
; #pragma unroll 16
;             for (int ks = 0; ks < K / 64; ++ks) {
;                 const bf16x8 af = *(const bf16x8*)(ap + ks * 32), bfv = *(const bf16x8*)(bp + ks * 32);
;                 tot = __builtin_amdgcn_mfma_f32_16x16x32_bf16(bfv, af, tot, 0, 0, 0);
;             }
	ds_bpermute_b32 v60, v134, v60
	ds_bpermute_b32 v61, v134, v61
	ds_bpermute_b32 v62, v134, v62
	ds_bpermute_b32 v63, v134, v63
	ds_bpermute_b32 v72, v134, v72
	ds_bpermute_b32 v73, v134, v73
	ds_bpermute_b32 v74, v134, v74
	ds_bpermute_b32 v75, v134, v75
	s_waitcnt lgkmcnt(0)
	v_mfma_f32_16x16x32_bf16 v[16:19], v[60:63], v[72:75], v[16:19]
	global_load_dwordx4 v[60:63], v[0:1], off offset:1920
	global_load_dwordx4 v[72:75], v[0:1], off offset:1984
	s_waitcnt vmcnt(21)
	ds_bpermute_b32 v68, v134, v68
	ds_bpermute_b32 v69, v134, v69
	ds_bpermute_b32 v70, v134, v70
	ds_bpermute_b32 v71, v134, v71
	ds_bpermute_b32 v80, v134, v80
	ds_bpermute_b32 v81, v134, v81
	ds_bpermute_b32 v82, v134, v82
	ds_bpermute_b32 v83, v134, v83
	s_waitcnt lgkmcnt(0)
	v_mfma_f32_16x16x32_bf16 v[16:19], v[68:71], v[80:83], v[16:19]
	global_load_dwordx4 v[68:71], v[2:3], off offset:2048
	global_load_dwordx4 v[80:83], v[0:1], off offset:2048
	s_waitcnt vmcnt(22)
	ds_bpermute_b32 v76, v134, v76
	ds_bpermute_b32 v77, v134, v77
	ds_bpermute_b32 v78, v134, v78
	ds_bpermute_b32 v79, v134, v79
	ds_bpermute_b32 v88, v134, v88
	ds_bpermute_b32 v89, v134, v89
	ds_bpermute_b32 v90, v134, v90
	ds_bpermute_b32 v91, v134, v91
	s_waitcnt lgkmcnt(0)
	v_mfma_f32_16x16x32_bf16 v[16:19], v[76:79], v[88:91], v[16:19]
	global_load_dwordx4 v[76:79], v[2:3], off offset:2112
	s_waitcnt vmcnt(21)
	ds_bpermute_b32 v84, v134, v84
	ds_bpermute_b32 v85, v134, v85
	ds_bpermute_b32 v86, v134, v86
	ds_bpermute_b32 v87, v134, v87
	ds_bpermute_b32 v92, v134, v92
	ds_bpermute_b32 v93, v134, v93
	ds_bpermute_b32 v94, v134, v94
	ds_bpermute_b32 v95, v134, v95
	s_waitcnt lgkmcnt(0)
	v_mfma_f32_16x16x32_bf16 v[16:19], v[84:87], v[92:95], v[16:19]
	global_load_dwordx4 v[84:87], v[0:1], off offset:2112
	global_load_dwordx4 v[88:91], v[2:3], off offset:2176
	global_load_dwordx4 v[92:95], v[2:3], off offset:2240
	s_waitcnt vmcnt(22)
	ds_bpermute_b32 v96, v134, v96
	ds_bpermute_b32 v97, v134, v97
	ds_bpermute_b32 v98, v134, v98
	ds_bpermute_b32 v99, v134, v99
	ds_bpermute_b32 v100, v134, v100
	ds_bpermute_b32 v101, v134, v101
	ds_bpermute_b32 v102, v134, v102
	ds_bpermute_b32 v103, v134, v103
	s_waitcnt lgkmcnt(0)
	v_mfma_f32_16x16x32_bf16 v[16:19], v[96:99], v[100:103], v[16:19]
	s_waitcnt vmcnt(19)
	ds_bpermute_b32 v20, v134, v20
	ds_bpermute_b32 v21, v134, v21
	ds_bpermute_b32 v22, v134, v22
	ds_bpermute_b32 v23, v134, v23
	ds_bpermute_b32 v108, v134, v108
	ds_bpermute_b32 v109, v134, v109
	ds_bpermute_b32 v110, v134, v110
	ds_bpermute_b32 v111, v134, v111
	s_waitcnt lgkmcnt(0)
	v_mfma_f32_16x16x32_bf16 v[16:19], v[20:23], v[108:111], v[16:19]
	global_load_dwordx4 v[20:23], v[0:1], off offset:2176
	global_load_dwordx4 v[96:99], v[0:1], off offset:2240
	s_waitcnt vmcnt(20)
	ds_bpermute_b32 v104, v134, v104
	ds_bpermute_b32 v105, v134, v105
	ds_bpermute_b32 v106, v134, v106
	ds_bpermute_b32 v107, v134, v107
	ds_bpermute_b32 v112, v134, v112
	ds_bpermute_b32 v113, v134, v113
	ds_bpermute_b32 v114, v134, v114
	ds_bpermute_b32 v115, v134, v115
	s_waitcnt lgkmcnt(0)
	v_mfma_f32_16x16x32_bf16 v[16:19], v[104:107], v[112:115], v[16:19]
	global_load_dwordx4 v[100:103], v[2:3], off offset:2304
	global_load_dwordx4 v[104:107], v[0:1], off offset:2304
	s_waitcnt vmcnt(20)
	ds_bpermute_b32 v24, v134, v24
	ds_bpermute_b32 v25, v134, v25
	ds_bpermute_b32 v26, v134, v26
	ds_bpermute_b32 v27, v134, v27
	ds_bpermute_b32 v28, v134, v28
	ds_bpermute_b32 v29, v134, v29
	ds_bpermute_b32 v30, v134, v30
	ds_bpermute_b32 v31, v134, v31
	s_waitcnt lgkmcnt(0)
	v_mfma_f32_16x16x32_bf16 v[16:19], v[24:27], v[28:31], v[16:19]
	global_load_dwordx4 v[24:27], v[2:3], off offset:2368
	global_load_dwordx4 v[28:31], v[0:1], off offset:2368
	s_waitcnt vmcnt(20)
	ds_bpermute_b32 v32, v134, v32
	ds_bpermute_b32 v33, v134, v33
	ds_bpermute_b32 v34, v134, v34
	ds_bpermute_b32 v35, v134, v35
	ds_bpermute_b32 v40, v134, v40
	ds_bpermute_b32 v41, v134, v41
	ds_bpermute_b32 v42, v134, v42
	ds_bpermute_b32 v43, v134, v43
	s_waitcnt lgkmcnt(0)
	v_mfma_f32_16x16x32_bf16 v[16:19], v[32:35], v[40:43], v[16:19]
	global_load_dwordx4 v[32:35], v[2:3], off offset:2432
	global_load_dwordx4 v[40:43], v[2:3], off offset:2496
	s_waitcnt vmcnt(19)
	ds_bpermute_b32 v36, v134, v36
	ds_bpermute_b32 v37, v134, v37
	ds_bpermute_b32 v38, v134, v38
	ds_bpermute_b32 v39, v134, v39
	ds_bpermute_b32 v44, v134, v44
	ds_bpermute_b32 v45, v134, v45
	ds_bpermute_b32 v46, v134, v46
	ds_bpermute_b32 v47, v134, v47
	s_waitcnt lgkmcnt(0)
	v_mfma_f32_16x16x32_bf16 v[16:19], v[36:39], v[44:47], v[16:19]
	global_load_dwordx4 v[36:39], v[0:1], off offset:2432
	global_load_dwordx4 v[44:47], v[0:1], off offset:2496
	s_waitcnt vmcnt(20)
	ds_bpermute_b32 v48, v134, v48
	ds_bpermute_b32 v49, v134, v49
	ds_bpermute_b32 v50, v134, v50
	ds_bpermute_b32 v51, v134, v51
	ds_bpermute_b32 v56, v134, v56
	ds_bpermute_b32 v57, v134, v57
	ds_bpermute_b32 v58, v134, v58
	ds_bpermute_b32 v59, v134, v59
	s_waitcnt lgkmcnt(0)
	v_mfma_f32_16x16x32_bf16 v[16:19], v[48:51], v[56:59], v[16:19]
	global_load_dwordx4 v[48:51], v[2:3], off offset:2560
	global_load_dwordx4 v[56:59], v[2:3], off offset:2624
	s_waitcnt vmcnt(19)
	ds_bpermute_b32 v52, v134, v52
	ds_bpermute_b32 v53, v134, v53
	ds_bpermute_b32 v54, v134, v54
	ds_bpermute_b32 v55, v134, v55
	ds_bpermute_b32 v60, v134, v60
	ds_bpermute_b32 v61, v134, v61
	ds_bpermute_b32 v62, v134, v62
	ds_bpermute_b32 v63, v134, v63
	s_waitcnt lgkmcnt(0)
	v_mfma_f32_16x16x32_bf16 v[16:19], v[52:55], v[60:63], v[16:19]
	global_load_dwordx4 v[52:55], v[0:1], off offset:2560
	global_load_dwordx4 v[60:63], v[0:1], off offset:2624
	s_waitcnt vmcnt(20)
; template <int MODE> ...
;     ...
; #pragma unroll 16
;             for (int ks = 0; ks < K / 64; ++ks) {
;                 const bf16x8 af = *(const bf16x8*)(ap + ks * 32), bfv = *(const bf16x8*)(bp + ks * 32);
;                 tot = __builtin_amdgcn_mfma_f32_16x16x32_bf16(bfv, af, tot, 0, 0, 0);
;             }
	ds_bpermute_b32 v64, v134, v64
	ds_bpermute_b32 v65, v134, v65
	ds_bpermute_b32 v66, v134, v66
	ds_bpermute_b32 v67, v134, v67
	ds_bpermute_b32 v72, v134, v72
	ds_bpermute_b32 v73, v134, v73
	ds_bpermute_b32 v74, v134, v74
	ds_bpermute_b32 v75, v134, v75
	s_waitcnt lgkmcnt(0)
	v_mfma_f32_16x16x32_bf16 v[16:19], v[64:67], v[72:75], v[16:19]
	global_load_dwordx4 v[64:67], v[2:3], off offset:2688
	global_load_dwordx4 v[72:75], v[0:1], off offset:2688
	s_waitcnt vmcnt(20)
	ds_bpermute_b32 v68, v134, v68
	ds_bpermute_b32 v69, v134, v69
	ds_bpermute_b32 v70, v134, v70
	ds_bpermute_b32 v71, v134, v71
	ds_bpermute_b32 v80, v134, v80
	ds_bpermute_b32 v81, v134, v81
	ds_bpermute_b32 v82, v134, v82
	ds_bpermute_b32 v83, v134, v83
	s_waitcnt lgkmcnt(0)
	v_mfma_f32_16x16x32_bf16 v[16:19], v[68:71], v[80:83], v[16:19]
	global_load_dwordx4 v[68:71], v[2:3], off offset:2752
	s_waitcnt vmcnt(19)
	ds_bpermute_b32 v76, v134, v76
	ds_bpermute_b32 v77, v134, v77
	ds_bpermute_b32 v78, v134, v78
	ds_bpermute_b32 v79, v134, v79
	ds_bpermute_b32 v84, v134, v84
	ds_bpermute_b32 v85, v134, v85
	ds_bpermute_b32 v86, v134, v86
	ds_bpermute_b32 v87, v134, v87
	s_waitcnt lgkmcnt(0)
	v_mfma_f32_16x16x32_bf16 v[16:19], v[76:79], v[84:87], v[16:19]
	global_load_dwordx4 v[76:79], v[0:1], off offset:2752
	s_waitcnt vmcnt(17)
	ds_bpermute_b32 v88, v134, v88
	ds_bpermute_b32 v89, v134, v89
	ds_bpermute_b32 v90, v134, v90
	ds_bpermute_b32 v91, v134, v91
	ds_bpermute_b32 v20, v134, v20
	ds_bpermute_b32 v21, v134, v21
	ds_bpermute_b32 v22, v134, v22
	ds_bpermute_b32 v23, v134, v23
	s_waitcnt lgkmcnt(0)
	v_mfma_f32_16x16x32_bf16 v[16:19], v[88:91], v[20:23], v[16:19]
	global_load_dwordx4 v[20:23], v[2:3], off offset:2816
	global_load_dwordx4 v[80:83], v[2:3], off offset:2880
	global_load_dwordx4 v[84:87], v[0:1], off offset:2816
	global_load_dwordx4 v[88:91], v[0:1], off offset:2880
	s_waitcnt vmcnt(20)
	ds_bpermute_b32 v92, v134, v92
	ds_bpermute_b32 v93, v134, v93
	ds_bpermute_b32 v94, v134, v94
	ds_bpermute_b32 v95, v134, v95
	ds_bpermute_b32 v96, v134, v96
	ds_bpermute_b32 v97, v134, v97
	ds_bpermute_b32 v98, v134, v98
	ds_bpermute_b32 v99, v134, v99
	s_waitcnt lgkmcnt(0)
	v_mfma_f32_16x16x32_bf16 v[16:19], v[92:95], v[96:99], v[16:19]
	global_load_dwordx4 v[92:95], v[2:3], off offset:2944
	global_load_dwordx4 v[96:99], v[0:1], off offset:2944
	s_waitcnt vmcnt(20)
	ds_bpermute_b32 v100, v134, v100
	ds_bpermute_b32 v101, v134, v101
	ds_bpermute_b32 v102, v134, v102
	ds_bpermute_b32 v103, v134, v103
	ds_bpermute_b32 v104, v134, v104
	ds_bpermute_b32 v105, v134, v105
	ds_bpermute_b32 v106, v134, v106
	ds_bpermute_b32 v107, v134, v107
	s_waitcnt lgkmcnt(0)
	v_mfma_f32_16x16x32_bf16 v[16:19], v[100:103], v[104:107], v[16:19]
	s_waitcnt vmcnt(18)
	ds_bpermute_b32 v24, v134, v24
	ds_bpermute_b32 v25, v134, v25
	ds_bpermute_b32 v26, v134, v26
	ds_bpermute_b32 v27, v134, v27
	ds_bpermute_b32 v28, v134, v28
	ds_bpermute_b32 v29, v134, v29
	ds_bpermute_b32 v30, v134, v30
	ds_bpermute_b32 v31, v134, v31
	s_waitcnt lgkmcnt(0)
	v_mfma_f32_16x16x32_bf16 v[16:19], v[24:27], v[28:31], v[16:19]
	global_load_dwordx4 v[24:27], v[2:3], off offset:3008
	global_load_dwordx4 v[28:31], v[0:1], off offset:3008
	s_waitcnt vmcnt(17)
	ds_bpermute_b32 v32, v134, v32
	ds_bpermute_b32 v33, v134, v33
	ds_bpermute_b32 v34, v134, v34
	ds_bpermute_b32 v35, v134, v35
	ds_bpermute_b32 v36, v134, v36
	ds_bpermute_b32 v37, v134, v37
	ds_bpermute_b32 v38, v134, v38
	ds_bpermute_b32 v39, v134, v39
	s_waitcnt lgkmcnt(0)
	v_mfma_f32_16x16x32_bf16 v[16:19], v[32:35], v[36:39], v[16:19]
	global_load_dwordx4 v[32:35], v[2:3], off offset:3072
	global_load_dwordx4 v[36:39], v[2:3], off offset:3136
	s_waitcnt vmcnt(18)
	ds_bpermute_b32 v40, v134, v40
	ds_bpermute_b32 v41, v134, v41
	ds_bpermute_b32 v42, v134, v42
	ds_bpermute_b32 v43, v134, v43
	ds_bpermute_b32 v44, v134, v44
	ds_bpermute_b32 v45, v134, v45
	ds_bpermute_b32 v46, v134, v46
	ds_bpermute_b32 v47, v134, v47
	s_waitcnt lgkmcnt(0)
	v_mfma_f32_16x16x32_bf16 v[16:19], v[40:43], v[44:47], v[16:19]
	global_load_dwordx4 v[40:43], v[0:1], off offset:3072
	global_load_dwordx4 v[44:47], v[0:1], off offset:3136
	s_waitcnt vmcnt(17)
	ds_bpermute_b32 v48, v134, v48
	ds_bpermute_b32 v49, v134, v49
	ds_bpermute_b32 v50, v134, v50
	ds_bpermute_b32 v51, v134, v51
	ds_bpermute_b32 v52, v134, v52
	ds_bpermute_b32 v53, v134, v53
	ds_bpermute_b32 v54, v134, v54
	ds_bpermute_b32 v55, v134, v55
	s_waitcnt lgkmcnt(0)
	v_mfma_f32_16x16x32_bf16 v[16:19], v[48:51], v[52:55], v[16:19]
	global_load_dwordx4 v[48:51], v[2:3], off offset:3200
	global_load_dwordx4 v[52:55], v[2:3], off offset:3264
	s_waitcnt vmcnt(18)
	ds_bpermute_b32 v56, v134, v56
	ds_bpermute_b32 v57, v134, v57
	ds_bpermute_b32 v58, v134, v58
	ds_bpermute_b32 v59, v134, v59
	ds_bpermute_b32 v60, v134, v60
	ds_bpermute_b32 v61, v134, v61
	ds_bpermute_b32 v62, v134, v62
	ds_bpermute_b32 v63, v134, v63
	s_waitcnt lgkmcnt(0)
	v_mfma_f32_16x16x32_bf16 v[16:19], v[56:59], v[60:63], v[16:19]
	global_load_dwordx4 v[56:59], v[0:1], off offset:3200
	global_load_dwordx4 v[60:63], v[0:1], off offset:3264
	s_waitcnt vmcnt(18)
	ds_bpermute_b32 v64, v134, v64
	ds_bpermute_b32 v65, v134, v65
	ds_bpermute_b32 v66, v134, v66
	ds_bpermute_b32 v67, v134, v67
	ds_bpermute_b32 v72, v134, v72
	ds_bpermute_b32 v73, v134, v73
	ds_bpermute_b32 v74, v134, v74
	ds_bpermute_b32 v75, v134, v75
	s_waitcnt lgkmcnt(0)
	v_mfma_f32_16x16x32_bf16 v[16:19], v[64:67], v[72:75], v[16:19]
	global_load_dwordx4 v[64:67], v[2:3], off offset:3328
	s_waitcnt vmcnt(17)
; template <int MODE> ...
;     ...
; #pragma unroll 16
;             for (int ks = 0; ks < K / 64; ++ks) {
;                 const bf16x8 af = *(const bf16x8*)(ap + ks * 32), bfv = *(const bf16x8*)(bp + ks * 32);
;                 tot = __builtin_amdgcn_mfma_f32_16x16x32_bf16(bfv, af, tot, 0, 0, 0);
;             }
	ds_bpermute_b32 v68, v134, v68
	ds_bpermute_b32 v69, v134, v69
	ds_bpermute_b32 v70, v134, v70
	ds_bpermute_b32 v71, v134, v71
	ds_bpermute_b32 v76, v134, v76
	ds_bpermute_b32 v77, v134, v77
	ds_bpermute_b32 v78, v134, v78
	ds_bpermute_b32 v79, v134, v79
	s_waitcnt lgkmcnt(0)
	v_mfma_f32_16x16x32_bf16 v[16:19], v[68:71], v[76:79], v[16:19]
	global_load_dwordx4 v[68:71], v[0:1], off offset:3328
	s_waitcnt vmcnt(15)
	ds_bpermute_b32 v20, v134, v20
	ds_bpermute_b32 v21, v134, v21
	ds_bpermute_b32 v22, v134, v22
	ds_bpermute_b32 v23, v134, v23
	ds_bpermute_b32 v84, v134, v84
	ds_bpermute_b32 v85, v134, v85
	ds_bpermute_b32 v86, v134, v86
	ds_bpermute_b32 v87, v134, v87
	s_waitcnt lgkmcnt(0)
	v_mfma_f32_16x16x32_bf16 v[16:19], v[20:23], v[84:87], v[16:19]
	global_load_dwordx4 v[20:23], v[2:3], off offset:3392
	global_load_dwordx4 v[72:75], v[0:1], off offset:3392
	s_waitcnt vmcnt(16)
	ds_bpermute_b32 v80, v134, v80
	ds_bpermute_b32 v81, v134, v81
	ds_bpermute_b32 v82, v134, v82
	ds_bpermute_b32 v83, v134, v83
	ds_bpermute_b32 v88, v134, v88
	ds_bpermute_b32 v89, v134, v89
	ds_bpermute_b32 v90, v134, v90
	ds_bpermute_b32 v91, v134, v91
	s_waitcnt lgkmcnt(0)
	v_mfma_f32_16x16x32_bf16 v[16:19], v[80:83], v[88:91], v[16:19]
	global_load_dwordx4 v[76:79], v[2:3], off offset:3456
	global_load_dwordx4 v[80:83], v[2:3], off offset:3520
	global_load_dwordx4 v[84:87], v[0:1], off offset:3456
	global_load_dwordx4 v[88:91], v[0:1], off offset:3520
	s_waitcnt vmcnt(18)
	ds_bpermute_b32 v92, v134, v92
	ds_bpermute_b32 v93, v134, v93
	ds_bpermute_b32 v94, v134, v94
	ds_bpermute_b32 v95, v134, v95
	ds_bpermute_b32 v96, v134, v96
	ds_bpermute_b32 v97, v134, v97
	ds_bpermute_b32 v98, v134, v98
	ds_bpermute_b32 v99, v134, v99
	s_waitcnt lgkmcnt(0)
	v_mfma_f32_16x16x32_bf16 v[16:19], v[92:95], v[96:99], v[16:19]
	s_waitcnt vmcnt(16)
	ds_bpermute_b32 v24, v134, v24
	ds_bpermute_b32 v25, v134, v25
	ds_bpermute_b32 v26, v134, v26
	ds_bpermute_b32 v27, v134, v27
	ds_bpermute_b32 v28, v134, v28
	ds_bpermute_b32 v29, v134, v29
	ds_bpermute_b32 v30, v134, v30
	ds_bpermute_b32 v31, v134, v31
	s_waitcnt lgkmcnt(0)
	v_mfma_f32_16x16x32_bf16 v[16:19], v[24:27], v[28:31], v[16:19]
	global_load_dwordx4 v[24:27], v[2:3], off offset:3584
	global_load_dwordx4 v[28:31], v[0:1], off offset:3584
	s_waitcnt vmcnt(15)
	ds_bpermute_b32 v32, v134, v32
	ds_bpermute_b32 v33, v134, v33
	ds_bpermute_b32 v34, v134, v34
	ds_bpermute_b32 v35, v134, v35
	ds_bpermute_b32 v40, v134, v40
	ds_bpermute_b32 v41, v134, v41
	ds_bpermute_b32 v42, v134, v42
	ds_bpermute_b32 v43, v134, v43
	s_waitcnt lgkmcnt(0)
	v_mfma_f32_16x16x32_bf16 v[16:19], v[32:35], v[40:43], v[16:19]
	global_load_dwordx4 v[32:35], v[2:3], off offset:3648
	global_load_dwordx4 v[40:43], v[0:1], off offset:3648
	s_waitcnt vmcnt(16)
	ds_bpermute_b32 v36, v134, v36
	ds_bpermute_b32 v37, v134, v37
	ds_bpermute_b32 v38, v134, v38
	ds_bpermute_b32 v39, v134, v39
	ds_bpermute_b32 v44, v134, v44
	ds_bpermute_b32 v45, v134, v45
	ds_bpermute_b32 v46, v134, v46
	ds_bpermute_b32 v47, v134, v47
	s_waitcnt lgkmcnt(0)
	v_mfma_f32_16x16x32_bf16 v[16:19], v[36:39], v[44:47], v[16:19]
	global_load_dwordx4 v[36:39], v[2:3], off offset:3712
	global_load_dwordx4 v[44:47], v[2:3], off offset:3776
	s_waitcnt vmcnt(15)
	ds_bpermute_b32 v48, v134, v48
	ds_bpermute_b32 v49, v134, v49
	ds_bpermute_b32 v50, v134, v50
	ds_bpermute_b32 v51, v134, v51
	ds_bpermute_b32 v56, v134, v56
	ds_bpermute_b32 v57, v134, v57
	ds_bpermute_b32 v58, v134, v58
	ds_bpermute_b32 v59, v134, v59
	s_waitcnt lgkmcnt(0)
	v_mfma_f32_16x16x32_bf16 v[16:19], v[48:51], v[56:59], v[16:19]
	global_load_dwordx4 v[48:51], v[0:1], off offset:3712
	global_load_dwordx4 v[56:59], v[0:1], off offset:3776
	s_waitcnt vmcnt(16)
	ds_bpermute_b32 v52, v134, v52
	ds_bpermute_b32 v53, v134, v53
	ds_bpermute_b32 v54, v134, v54
	ds_bpermute_b32 v55, v134, v55
	ds_bpermute_b32 v60, v134, v60
	ds_bpermute_b32 v61, v134, v61
	ds_bpermute_b32 v62, v134, v62
	ds_bpermute_b32 v63, v134, v63
	s_waitcnt lgkmcnt(0)
	v_mfma_f32_16x16x32_bf16 v[16:19], v[52:55], v[60:63], v[16:19]
	global_load_dwordx4 v[52:55], v[2:3], off offset:3840
	global_load_dwordx4 v[60:63], v[0:1], off offset:3840
	s_waitcnt vmcnt(16)
	ds_bpermute_b32 v64, v134, v64
	ds_bpermute_b32 v65, v134, v65
	ds_bpermute_b32 v66, v134, v66
	ds_bpermute_b32 v67, v134, v67
	ds_bpermute_b32 v68, v134, v68
	ds_bpermute_b32 v69, v134, v69
	ds_bpermute_b32 v70, v134, v70
	ds_bpermute_b32 v71, v134, v71
	s_waitcnt lgkmcnt(0)
	v_mfma_f32_16x16x32_bf16 v[16:19], v[64:67], v[68:71], v[16:19]
	s_waitcnt vmcnt(14)
	ds_bpermute_b32 v20, v134, v20
	ds_bpermute_b32 v21, v134, v21
	ds_bpermute_b32 v22, v134, v22
	ds_bpermute_b32 v23, v134, v23
	ds_bpermute_b32 v72, v134, v72
	ds_bpermute_b32 v73, v134, v73
	ds_bpermute_b32 v74, v134, v74
	ds_bpermute_b32 v75, v134, v75
	s_waitcnt lgkmcnt(0)
	v_mfma_f32_16x16x32_bf16 v[16:19], v[20:23], v[72:75], v[16:19]
	global_load_dwordx4 v[20:23], v[0:1], off offset:3904
	global_load_dwordx4 v[64:67], v[0:1], off offset:3968
	global_load_dwordx4 v[68:71], v[0:1], off offset:4032
	s_waitcnt vmcnt(14)
	ds_bpermute_b32 v76, v134, v76
	ds_bpermute_b32 v77, v134, v77
	ds_bpermute_b32 v78, v134, v78
	ds_bpermute_b32 v79, v134, v79
	ds_bpermute_b32 v84, v134, v84
	ds_bpermute_b32 v85, v134, v85
	ds_bpermute_b32 v86, v134, v86
	ds_bpermute_b32 v87, v134, v87
	s_waitcnt lgkmcnt(0)
	v_mfma_f32_16x16x32_bf16 v[16:19], v[76:79], v[84:87], v[16:19]
	global_load_dwordx4 v[72:75], v[2:3], off offset:3904
	global_load_dwordx4 v[76:79], v[2:3], off offset:3968
	global_load_dwordx4 v[84:87], v[2:3], off offset:4032
	s_waitcnt vmcnt(16)
; template <int MODE> ...
;     ...
; #pragma unroll 16
;             for (int ks = 0; ks < K / 64; ++ks) {
;                 const bf16x8 af = *(const bf16x8*)(ap + ks * 32), bfv = *(const bf16x8*)(bp + ks * 32);
;                 tot = __builtin_amdgcn_mfma_f32_16x16x32_bf16(bfv, af, tot, 0, 0, 0);
;             }
	ds_bpermute_b32 v80, v134, v80
	ds_bpermute_b32 v81, v134, v81
	ds_bpermute_b32 v82, v134, v82
	ds_bpermute_b32 v83, v134, v83
	ds_bpermute_b32 v88, v134, v88
	ds_bpermute_b32 v89, v134, v89
	ds_bpermute_b32 v90, v134, v90
	ds_bpermute_b32 v91, v134, v91
	s_waitcnt lgkmcnt(0)
	v_mfma_f32_16x16x32_bf16 v[16:19], v[80:83], v[88:91], v[16:19]
	v_add_co_u32_e32 v88, vcc, s19, v2
	s_nop 1
	v_addc_co_u32_e32 v89, vcc, 0, v3, vcc
	global_load_dwordx4 v[80:83], v[88:89], off
	v_add_co_u32_e32 v90, vcc, s19, v0
	s_waitcnt vmcnt(15)
	ds_bpermute_b32 v24, v134, v24
	ds_bpermute_b32 v25, v134, v25
	ds_bpermute_b32 v26, v134, v26
	ds_bpermute_b32 v27, v134, v27
	ds_bpermute_b32 v28, v134, v28
	ds_bpermute_b32 v29, v134, v29
	ds_bpermute_b32 v30, v134, v30
	ds_bpermute_b32 v31, v134, v31
	s_waitcnt lgkmcnt(0)
	v_mfma_f32_16x16x32_bf16 v[16:19], v[24:27], v[28:31], v[16:19]
	v_addc_co_u32_e32 v91, vcc, 0, v1, vcc
	global_load_dwordx4 v[0:3], v[88:89], off offset:64
	global_load_dwordx4 v[24:27], v[90:91], off
	global_load_dwordx4 v[28:31], v[90:91], off offset:64
	s_waitcnt vmcnt(16)
	ds_bpermute_b32 v32, v134, v32
	ds_bpermute_b32 v33, v134, v33
	ds_bpermute_b32 v34, v134, v34
	ds_bpermute_b32 v35, v134, v35
	ds_bpermute_b32 v40, v134, v40
	ds_bpermute_b32 v41, v134, v41
	ds_bpermute_b32 v42, v134, v42
	ds_bpermute_b32 v43, v134, v43
	s_waitcnt lgkmcnt(0)
	v_mfma_f32_16x16x32_bf16 v[16:19], v[32:35], v[40:43], v[16:19]
	s_and_b64 vcc, exec, s[4:5]
	s_waitcnt vmcnt(13)
	ds_bpermute_b32 v36, v134, v36
	ds_bpermute_b32 v37, v134, v37
	ds_bpermute_b32 v38, v134, v38
	ds_bpermute_b32 v39, v134, v39
	ds_bpermute_b32 v48, v134, v48
	ds_bpermute_b32 v49, v134, v49
	ds_bpermute_b32 v50, v134, v50
	ds_bpermute_b32 v51, v134, v51
	s_waitcnt lgkmcnt(0)
	v_mfma_f32_16x16x32_bf16 v[16:19], v[36:39], v[48:51], v[16:19]
	global_load_dwordx4 v[32:35], v[88:89], off offset:128
	global_load_dwordx4 v[36:39], v[90:91], off offset:128
	global_load_dwordx4 v[40:43], v[88:89], off offset:192
	s_waitcnt vmcnt(15)
	ds_bpermute_b32 v44, v134, v44
	ds_bpermute_b32 v45, v134, v45
	ds_bpermute_b32 v46, v134, v46
	ds_bpermute_b32 v47, v134, v47
	ds_bpermute_b32 v56, v134, v56
	ds_bpermute_b32 v57, v134, v57
	ds_bpermute_b32 v58, v134, v58
	ds_bpermute_b32 v59, v134, v59
	s_waitcnt lgkmcnt(0)
	v_mfma_f32_16x16x32_bf16 v[16:19], v[44:47], v[56:59], v[16:19]
	global_load_dwordx4 v[44:47], v[90:91], off offset:192
	s_waitcnt vmcnt(14)
	ds_bpermute_b32 v52, v134, v52
	ds_bpermute_b32 v53, v134, v53
	ds_bpermute_b32 v54, v134, v54
	ds_bpermute_b32 v55, v134, v55
	ds_bpermute_b32 v60, v134, v60
	ds_bpermute_b32 v61, v134, v61
	ds_bpermute_b32 v62, v134, v62
	ds_bpermute_b32 v63, v134, v63
	s_waitcnt lgkmcnt(0)
	v_mfma_f32_16x16x32_bf16 v[16:19], v[52:55], v[60:63], v[16:19]
	s_waitcnt vmcnt(10)
	ds_bpermute_b32 v72, v134, v72
	ds_bpermute_b32 v73, v134, v73
	ds_bpermute_b32 v74, v134, v74
	ds_bpermute_b32 v75, v134, v75
	ds_bpermute_b32 v20, v134, v20
	ds_bpermute_b32 v21, v134, v21
	ds_bpermute_b32 v22, v134, v22
	ds_bpermute_b32 v23, v134, v23
	s_waitcnt lgkmcnt(0)
	v_mfma_f32_16x16x32_bf16 v[16:19], v[72:75], v[20:23], v[16:19]
	global_load_dwordx4 v[20:23], v[88:89], off offset:256
	global_load_dwordx4 v[48:51], v[88:89], off offset:320
	global_load_dwordx4 v[52:55], v[90:91], off offset:256
	global_load_dwordx4 v[56:59], v[90:91], off offset:320
	s_waitcnt vmcnt(13)
	ds_bpermute_b32 v76, v134, v76
	ds_bpermute_b32 v77, v134, v77
	ds_bpermute_b32 v78, v134, v78
	ds_bpermute_b32 v79, v134, v79
	ds_bpermute_b32 v64, v134, v64
	ds_bpermute_b32 v65, v134, v65
	ds_bpermute_b32 v66, v134, v66
	ds_bpermute_b32 v67, v134, v67
	s_waitcnt lgkmcnt(0)
	v_mfma_f32_16x16x32_bf16 v[16:19], v[76:79], v[64:67], v[16:19]
	global_load_dwordx4 v[60:63], v[88:89], off offset:384
	global_load_dwordx4 v[64:67], v[88:89], off offset:448
	s_waitcnt vmcnt(14)
	ds_bpermute_b32 v84, v134, v84
	ds_bpermute_b32 v85, v134, v85
	ds_bpermute_b32 v86, v134, v86
	ds_bpermute_b32 v87, v134, v87
	ds_bpermute_b32 v68, v134, v68
	ds_bpermute_b32 v69, v134, v69
	ds_bpermute_b32 v70, v134, v70
	ds_bpermute_b32 v71, v134, v71
	s_waitcnt lgkmcnt(0)
	v_mfma_f32_16x16x32_bf16 v[16:19], v[84:87], v[68:71], v[16:19]
	s_waitcnt vmcnt(11)
	ds_bpermute_b32 v80, v134, v80
	ds_bpermute_b32 v81, v134, v81
	ds_bpermute_b32 v82, v134, v82
	ds_bpermute_b32 v83, v134, v83
	ds_bpermute_b32 v24, v134, v24
	ds_bpermute_b32 v25, v134, v25
	ds_bpermute_b32 v26, v134, v26
	ds_bpermute_b32 v27, v134, v27
	s_waitcnt lgkmcnt(0)
	v_mfma_f32_16x16x32_bf16 v[16:19], v[80:83], v[24:27], v[16:19]
	global_load_dwordx4 v[24:27], v[90:91], off offset:384
	global_load_dwordx4 v[68:71], v[90:91], off offset:448
	s_waitcnt vmcnt(12)
	ds_bpermute_b32 v0, v134, v0
	ds_bpermute_b32 v1, v134, v1
	ds_bpermute_b32 v2, v134, v2
	ds_bpermute_b32 v3, v134, v3
	ds_bpermute_b32 v28, v134, v28
	ds_bpermute_b32 v29, v134, v29
	ds_bpermute_b32 v30, v134, v30
	ds_bpermute_b32 v31, v134, v31
	s_waitcnt lgkmcnt(0)
	v_mfma_f32_16x16x32_bf16 v[0:3], v[0:3], v[28:31], v[16:19]
	s_nop 3
	global_load_dwordx4 v[16:19], v[88:89], off offset:512
	global_load_dwordx4 v[28:31], v[90:91], off offset:512
	s_waitcnt vmcnt(12)
	ds_bpermute_b32 v32, v134, v32
	ds_bpermute_b32 v33, v134, v33
	ds_bpermute_b32 v34, v134, v34
	ds_bpermute_b32 v35, v134, v35
	ds_bpermute_b32 v36, v134, v36
	ds_bpermute_b32 v37, v134, v37
	ds_bpermute_b32 v38, v134, v38
	ds_bpermute_b32 v39, v134, v39
	s_waitcnt lgkmcnt(0)
	v_mfma_f32_16x16x32_bf16 v[0:3], v[32:35], v[36:39], v[0:3]
	global_load_dwordx4 v[32:35], v[88:89], off offset:576
	global_load_dwordx4 v[36:39], v[90:91], off offset:576
	s_waitcnt vmcnt(12)
; template <int MODE> ...
;     ...
; #pragma unroll 16
;             for (int ks = 0; ks < K / 64; ++ks) {
;                 const bf16x8 af = *(const bf16x8*)(ap + ks * 32), bfv = *(const bf16x8*)(bp + ks * 32);
;                 tot = __builtin_amdgcn_mfma_f32_16x16x32_bf16(bfv, af, tot, 0, 0, 0);
;             }
	ds_bpermute_b32 v40, v134, v40
	ds_bpermute_b32 v41, v134, v41
	ds_bpermute_b32 v42, v134, v42
	ds_bpermute_b32 v43, v134, v43
	ds_bpermute_b32 v44, v134, v44
	ds_bpermute_b32 v45, v134, v45
	ds_bpermute_b32 v46, v134, v46
	ds_bpermute_b32 v47, v134, v47
	s_waitcnt lgkmcnt(0)
	v_mfma_f32_16x16x32_bf16 v[0:3], v[40:43], v[44:47], v[0:3]
	s_waitcnt vmcnt(9)
	ds_bpermute_b32 v20, v134, v20
	ds_bpermute_b32 v21, v134, v21
	ds_bpermute_b32 v22, v134, v22
	ds_bpermute_b32 v23, v134, v23
	ds_bpermute_b32 v52, v134, v52
	ds_bpermute_b32 v53, v134, v53
	ds_bpermute_b32 v54, v134, v54
	ds_bpermute_b32 v55, v134, v55
	s_waitcnt lgkmcnt(0)
	v_mfma_f32_16x16x32_bf16 v[0:3], v[20:23], v[52:55], v[0:3]
	global_load_dwordx4 v[20:23], v[88:89], off offset:640
	global_load_dwordx4 v[40:43], v[88:89], off offset:704
	s_waitcnt vmcnt(10)
	ds_bpermute_b32 v48, v134, v48
	ds_bpermute_b32 v49, v134, v49
	ds_bpermute_b32 v50, v134, v50
	ds_bpermute_b32 v51, v134, v51
	ds_bpermute_b32 v56, v134, v56
	ds_bpermute_b32 v57, v134, v57
	ds_bpermute_b32 v58, v134, v58
	ds_bpermute_b32 v59, v134, v59
	s_waitcnt lgkmcnt(0)
	v_mfma_f32_16x16x32_bf16 v[0:3], v[48:51], v[56:59], v[0:3]
	global_load_dwordx4 v[44:47], v[90:91], off offset:640
	global_load_dwordx4 v[48:51], v[90:91], off offset:704
	s_waitcnt vmcnt(9)
	ds_bpermute_b32 v60, v134, v60
	ds_bpermute_b32 v61, v134, v61
	ds_bpermute_b32 v62, v134, v62
	ds_bpermute_b32 v63, v134, v63
	ds_bpermute_b32 v24, v134, v24
	ds_bpermute_b32 v25, v134, v25
	ds_bpermute_b32 v26, v134, v26
	ds_bpermute_b32 v27, v134, v27
	s_waitcnt lgkmcnt(0)
	v_mfma_f32_16x16x32_bf16 v[0:3], v[60:63], v[24:27], v[0:3]
	global_load_dwordx4 v[24:27], v[88:89], off offset:768
	global_load_dwordx4 v[52:55], v[88:89], off offset:832
	global_load_dwordx4 v[56:59], v[90:91], off offset:768
	global_load_dwordx4 v[60:63], v[90:91], off offset:832
	s_waitcnt vmcnt(12)
	ds_bpermute_b32 v64, v134, v64
	ds_bpermute_b32 v65, v134, v65
	ds_bpermute_b32 v66, v134, v66
	ds_bpermute_b32 v67, v134, v67
	ds_bpermute_b32 v68, v134, v68
	ds_bpermute_b32 v69, v134, v69
	ds_bpermute_b32 v70, v134, v70
	ds_bpermute_b32 v71, v134, v71
	s_waitcnt lgkmcnt(0)
	v_mfma_f32_16x16x32_bf16 v[0:3], v[64:67], v[68:71], v[0:3]
	s_waitcnt vmcnt(10)
	ds_bpermute_b32 v16, v134, v16
	ds_bpermute_b32 v17, v134, v17
	ds_bpermute_b32 v18, v134, v18
	ds_bpermute_b32 v19, v134, v19
	ds_bpermute_b32 v28, v134, v28
	ds_bpermute_b32 v29, v134, v29
	ds_bpermute_b32 v30, v134, v30
	ds_bpermute_b32 v31, v134, v31
	s_waitcnt lgkmcnt(0)
	v_mfma_f32_16x16x32_bf16 v[0:3], v[16:19], v[28:31], v[0:3]
	global_load_dwordx4 v[16:19], v[88:89], off offset:896
	global_load_dwordx4 v[28:31], v[90:91], off offset:896
	s_waitcnt vmcnt(10)
	ds_bpermute_b32 v32, v134, v32
	ds_bpermute_b32 v33, v134, v33
	ds_bpermute_b32 v34, v134, v34
	ds_bpermute_b32 v35, v134, v35
	ds_bpermute_b32 v36, v134, v36
	ds_bpermute_b32 v37, v134, v37
	ds_bpermute_b32 v38, v134, v38
	ds_bpermute_b32 v39, v134, v39
	s_waitcnt lgkmcnt(0)
	v_mfma_f32_16x16x32_bf16 v[0:3], v[32:35], v[36:39], v[0:3]
	s_waitcnt vmcnt(7)
	ds_bpermute_b32 v20, v134, v20
	ds_bpermute_b32 v21, v134, v21
	ds_bpermute_b32 v22, v134, v22
	ds_bpermute_b32 v23, v134, v23
	ds_bpermute_b32 v44, v134, v44
	ds_bpermute_b32 v45, v134, v45
	ds_bpermute_b32 v46, v134, v46
	ds_bpermute_b32 v47, v134, v47
	s_waitcnt lgkmcnt(0)
	v_mfma_f32_16x16x32_bf16 v[0:3], v[20:23], v[44:47], v[0:3]
	global_load_dwordx4 v[20:23], v[88:89], off offset:960
	global_load_dwordx4 v[32:35], v[90:91], off offset:960
	s_waitcnt vmcnt(8)
	ds_bpermute_b32 v40, v134, v40
	ds_bpermute_b32 v41, v134, v41
	ds_bpermute_b32 v42, v134, v42
	ds_bpermute_b32 v43, v134, v43
	ds_bpermute_b32 v48, v134, v48
	ds_bpermute_b32 v49, v134, v49
	ds_bpermute_b32 v50, v134, v50
	ds_bpermute_b32 v51, v134, v51
	s_waitcnt lgkmcnt(0)
	v_mfma_f32_16x16x32_bf16 v[0:3], v[40:43], v[48:51], v[0:3]
	global_load_dwordx4 v[36:39], v[88:89], off offset:1024
	global_load_dwordx4 v[40:43], v[88:89], off offset:1088
	s_waitcnt vmcnt(7)
	ds_bpermute_b32 v24, v134, v24
	ds_bpermute_b32 v25, v134, v25
	ds_bpermute_b32 v26, v134, v26
	ds_bpermute_b32 v27, v134, v27
	ds_bpermute_b32 v56, v134, v56
	ds_bpermute_b32 v57, v134, v57
	ds_bpermute_b32 v58, v134, v58
	ds_bpermute_b32 v59, v134, v59
	s_waitcnt lgkmcnt(0)
	v_mfma_f32_16x16x32_bf16 v[0:3], v[24:27], v[56:59], v[0:3]
	global_load_dwordx4 v[24:27], v[90:91], off offset:1024
	global_load_dwordx4 v[44:47], v[90:91], off offset:1088
	global_load_dwordx4 v[48:51], v[88:89], off offset:1152
	s_waitcnt vmcnt(9)
; template <int MODE> ...
;     ...
; #pragma unroll 16
;             for (int ks = 0; ks < K / 64; ++ks) {
;                 const bf16x8 af = *(const bf16x8*)(ap + ks * 32), bfv = *(const bf16x8*)(bp + ks * 32);
;                 tot = __builtin_amdgcn_mfma_f32_16x16x32_bf16(bfv, af, tot, 0, 0, 0);
;             }
;     ...
;         if (kh == 1) red[tw * 64 + lane] = tot;
	ds_bpermute_b32 v52, v134, v52
	ds_bpermute_b32 v53, v134, v53
	ds_bpermute_b32 v54, v134, v54
	ds_bpermute_b32 v55, v134, v55
	ds_bpermute_b32 v60, v134, v60
	ds_bpermute_b32 v61, v134, v61
	ds_bpermute_b32 v62, v134, v62
	ds_bpermute_b32 v63, v134, v63
	s_waitcnt lgkmcnt(0)
	v_mfma_f32_16x16x32_bf16 v[0:3], v[52:55], v[60:63], v[0:3]
	s_waitcnt vmcnt(7)
	ds_bpermute_b32 v16, v134, v16
	ds_bpermute_b32 v17, v134, v17
	ds_bpermute_b32 v18, v134, v18
	ds_bpermute_b32 v19, v134, v19
	ds_bpermute_b32 v28, v134, v28
	ds_bpermute_b32 v29, v134, v29
	ds_bpermute_b32 v30, v134, v30
	ds_bpermute_b32 v31, v134, v31
	s_waitcnt lgkmcnt(0)
	v_mfma_f32_16x16x32_bf16 v[0:3], v[16:19], v[28:31], v[0:3]
	global_load_dwordx4 v[16:19], v[90:91], off offset:1152
	s_waitcnt vmcnt(6)
	ds_bpermute_b32 v20, v134, v20
	ds_bpermute_b32 v21, v134, v21
	ds_bpermute_b32 v22, v134, v22
	ds_bpermute_b32 v23, v134, v23
	ds_bpermute_b32 v32, v134, v32
	ds_bpermute_b32 v33, v134, v33
	ds_bpermute_b32 v34, v134, v34
	ds_bpermute_b32 v35, v134, v35
	s_waitcnt lgkmcnt(0)
	v_mfma_f32_16x16x32_bf16 v[0:3], v[20:23], v[32:35], v[0:3]
	global_load_dwordx4 v[20:23], v[88:89], off offset:1216
	global_load_dwordx4 v[28:31], v[90:91], off offset:1216
	s_waitcnt vmcnt(5)
	ds_bpermute_b32 v36, v134, v36
	ds_bpermute_b32 v37, v134, v37
	ds_bpermute_b32 v38, v134, v38
	ds_bpermute_b32 v39, v134, v39
	ds_bpermute_b32 v24, v134, v24
	ds_bpermute_b32 v25, v134, v25
	ds_bpermute_b32 v26, v134, v26
	ds_bpermute_b32 v27, v134, v27
	s_waitcnt lgkmcnt(0)
	v_mfma_f32_16x16x32_bf16 v[0:3], v[36:39], v[24:27], v[0:3]
	global_load_dwordx4 v[24:27], v[88:89], off offset:1280
	global_load_dwordx4 v[32:35], v[90:91], off offset:1280
	global_load_dwordx4 v[36:39], v[88:89], off offset:1344
	s_waitcnt vmcnt(7)
	ds_bpermute_b32 v40, v134, v40
	ds_bpermute_b32 v41, v134, v41
	ds_bpermute_b32 v42, v134, v42
	ds_bpermute_b32 v43, v134, v43
	ds_bpermute_b32 v44, v134, v44
	ds_bpermute_b32 v45, v134, v45
	ds_bpermute_b32 v46, v134, v46
	ds_bpermute_b32 v47, v134, v47
	s_waitcnt lgkmcnt(0)
	v_mfma_f32_16x16x32_bf16 v[0:3], v[40:43], v[44:47], v[0:3]
	s_waitcnt vmcnt(5)
	ds_bpermute_b32 v48, v134, v48
	ds_bpermute_b32 v49, v134, v49
	ds_bpermute_b32 v50, v134, v50
	ds_bpermute_b32 v51, v134, v51
	ds_bpermute_b32 v16, v134, v16
	ds_bpermute_b32 v17, v134, v17
	ds_bpermute_b32 v18, v134, v18
	ds_bpermute_b32 v19, v134, v19
	s_waitcnt lgkmcnt(0)
	v_mfma_f32_16x16x32_bf16 v[0:3], v[48:51], v[16:19], v[0:3]
	global_load_dwordx4 v[16:19], v[90:91], off offset:1344
	s_waitcnt vmcnt(4)
	ds_bpermute_b32 v20, v134, v20
	ds_bpermute_b32 v21, v134, v21
	ds_bpermute_b32 v22, v134, v22
	ds_bpermute_b32 v23, v134, v23
	ds_bpermute_b32 v28, v134, v28
	ds_bpermute_b32 v29, v134, v29
	ds_bpermute_b32 v30, v134, v30
	ds_bpermute_b32 v31, v134, v31
	s_waitcnt lgkmcnt(0)
	v_mfma_f32_16x16x32_bf16 v[0:3], v[20:23], v[28:31], v[0:3]
	global_load_dwordx4 v[20:23], v[88:89], off offset:1408
	global_load_dwordx4 v[28:31], v[90:91], off offset:1408
	s_waitcnt vmcnt(4)
	ds_bpermute_b32 v24, v134, v24
	ds_bpermute_b32 v25, v134, v25
	ds_bpermute_b32 v26, v134, v26
	ds_bpermute_b32 v27, v134, v27
	ds_bpermute_b32 v32, v134, v32
	ds_bpermute_b32 v33, v134, v33
	ds_bpermute_b32 v34, v134, v34
	ds_bpermute_b32 v35, v134, v35
	s_waitcnt lgkmcnt(0)
	v_mfma_f32_16x16x32_bf16 v[0:3], v[24:27], v[32:35], v[0:3]
	global_load_dwordx4 v[24:27], v[88:89], off offset:1472
	s_waitcnt vmcnt(3)
	ds_bpermute_b32 v36, v134, v36
	ds_bpermute_b32 v37, v134, v37
	ds_bpermute_b32 v38, v134, v38
	ds_bpermute_b32 v39, v134, v39
	ds_bpermute_b32 v16, v134, v16
	ds_bpermute_b32 v17, v134, v17
	ds_bpermute_b32 v18, v134, v18
	ds_bpermute_b32 v19, v134, v19
	s_waitcnt lgkmcnt(0)
	v_mfma_f32_16x16x32_bf16 v[0:3], v[36:39], v[16:19], v[0:3]
	global_load_dwordx4 v[16:19], v[90:91], off offset:1472
	s_waitcnt vmcnt(2)
	ds_bpermute_b32 v20, v134, v20
	ds_bpermute_b32 v21, v134, v21
	ds_bpermute_b32 v22, v134, v22
	ds_bpermute_b32 v23, v134, v23
	ds_bpermute_b32 v28, v134, v28
	ds_bpermute_b32 v29, v134, v29
	ds_bpermute_b32 v30, v134, v30
	ds_bpermute_b32 v31, v134, v31
	s_waitcnt lgkmcnt(0)
	v_mfma_f32_16x16x32_bf16 v[0:3], v[20:23], v[28:31], v[0:3]
	s_waitcnt vmcnt(0)
	ds_bpermute_b32 v24, v134, v24
	ds_bpermute_b32 v25, v134, v25
	ds_bpermute_b32 v26, v134, v26
	ds_bpermute_b32 v27, v134, v27
	ds_bpermute_b32 v16, v134, v16
	ds_bpermute_b32 v17, v134, v17
	ds_bpermute_b32 v18, v134, v18
	ds_bpermute_b32 v19, v134, v19
	s_waitcnt lgkmcnt(0)
	v_mfma_f32_16x16x32_bf16 v[0:3], v[24:27], v[16:19], v[0:3]
	s_cbranch_vccnz .LBB0_1101
	s_nop 6
	ds_write_b128 v9, v[0:3]
